# v106 + merged vmcnt/lgkmcnt closing waits into one s_waitcnt at 36 K-loop sites
# baseline (speedup 1.0000x reference)
.LBB0_333:
	s_add_u32 s68, s56, s49
	s_addc_u32 s70, s57, 0
	s_add_u32 s64, s68, 0x100
	s_addc_u32 s65, s70, 0
	s_and_b64 s[62:63], s[60:61], exec
	s_cselect_b32 s65, s18, s65
	s_cselect_b32 s64, s19, s64
	s_add_u32 s49, s54, s49
	s_addc_u32 s62, s55, 0
	s_add_u32 s49, s49, 0x100
	s_addc_u32 s62, s62, 0
	s_add_i32 s80, 0, 0x10000
	s_and_b64 s[60:61], s[60:61], exec
	s_cselect_b32 s67, s33, s62
	s_cselect_b32 s66, s45, s49
	s_add_i32 s61, 0, 0x14000
	s_add_u32 s72, s68, 0x10080
	s_addc_u32 s73, s70, 0
	s_add_i32 s79, s80, s2
	s_add_i32 m0, s4, 0xc000
	s_add_i32 s82, s4, 0xe000
	s_add_i32 s76, s79, 0x2000
	s_add_u32 s70, s66, 0x10000
	v_add_u32_e32 v152, s80, v138
	v_add_u32_e32 v168, s61, v138
	s_addc_u32 s71, s67, 0
	s_add_i32 s78, s61, s2
	ds_read_b128 v[140:143], v152
	ds_read_b128 v[144:147], v152 offset:1024
	ds_read_b128 v[148:151], v152 offset:2048
	ds_read_b128 v[152:155], v152 offset:3072
	ds_read_b128 v[156:159], v168
	ds_read_b128 v[160:163], v168 offset:1024
	ds_read_b128 v[164:167], v168 offset:2048
	ds_read_b128 v[168:171], v168 offset:3072
	s_add_i32 s77, s78, 0x2000
	s_add_i32 s75, 0, 0x18000
	s_add_i32 s74, 0, 0x1c000
	s_add_u32 s62, s64, 0x10000
	s_addc_u32 s63, s65, 0
	s_add_i32 s68, s75, s2
	s_add_i32 s49, s68, 0x2000
	s_add_u32 s60, s66, 0x10080
	s_addc_u32 s61, s67, 0
	s_add_i32 s81, s74, s2
	s_add_i32 s80, s81, 0x2000
	v_lshl_add_u64 v[204:205], s[72:73], 0, v[136:137]
	ds_read_b128 v[172:175], v139
	ds_read_b128 v[176:179], v139 offset:1024
	ds_read_b128 v[180:183], v139 offset:2048
	ds_read_b128 v[184:187], v139 offset:3072
	ds_read_b128 v[188:191], v139 offset:4096
	ds_read_b128 v[192:195], v139 offset:5120
	ds_read_b128 v[196:199], v139 offset:6144
	ds_read_b128 v[214:217], v139 offset:7168
	s_setprio 1
	global_load_lds_dwordx4 v[204:205], off
	v_lshl_add_u64 v[204:205], s[72:73], 0, v[134:135]
	s_mov_b32 m0, s82
	s_nop 0
	global_load_lds_dwordx4 v[204:205], off
	s_waitcnt vmcnt(8) lgkmcnt(0)
	s_barrier
	v_mfma_f32_16x16x32_bf16 v[128:131], v[140:143], v[172:175], v[128:131]
	v_mfma_f32_16x16x32_bf16 v[124:127], v[148:151], v[172:175], v[124:127]
	v_mfma_f32_16x16x32_bf16 v[120:123], v[140:143], v[180:183], v[120:123]
	v_mfma_f32_16x16x32_bf16 v[116:119], v[148:151], v[180:183], v[116:119]
	v_mfma_f32_16x16x32_bf16 v[104:107], v[140:143], v[188:191], v[104:107]
	v_mfma_f32_16x16x32_bf16 v[100:103], v[148:151], v[188:191], v[100:103]
	v_mfma_f32_16x16x32_bf16 v[86:89], v[140:143], v[196:199], v[86:89]
	v_mfma_f32_16x16x32_bf16 v[82:85], v[148:151], v[196:199], v[82:85]
	v_mfma_f32_16x16x32_bf16 v[128:131], v[144:147], v[176:179], v[128:131]
	v_mfma_f32_16x16x32_bf16 v[124:127], v[152:155], v[176:179], v[124:127]
	v_mfma_f32_16x16x32_bf16 v[120:123], v[144:147], v[184:187], v[120:123]
	v_mfma_f32_16x16x32_bf16 v[116:119], v[152:155], v[184:187], v[116:119]
	v_mfma_f32_16x16x32_bf16 v[104:107], v[144:147], v[192:195], v[104:107]
	v_mfma_f32_16x16x32_bf16 v[100:103], v[152:155], v[192:195], v[100:103]
	v_mfma_f32_16x16x32_bf16 v[86:89], v[144:147], v[214:217], v[86:89]
	v_mfma_f32_16x16x32_bf16 v[82:85], v[152:155], v[214:217], v[82:85]
	s_setprio 0
	s_setprio 1
	v_mfma_f32_16x16x32_bf16 v[112:115], v[156:159], v[172:175], v[112:115]
	v_mfma_f32_16x16x32_bf16 v[108:111], v[164:167], v[172:175], v[108:111]
	v_mfma_f32_16x16x32_bf16 v[94:97], v[156:159], v[180:183], v[94:97]
	v_mfma_f32_16x16x32_bf16 v[90:93], v[164:167], v[180:183], v[90:93]
	v_mfma_f32_16x16x32_bf16 v[78:81], v[156:159], v[188:191], v[78:81]
	v_mfma_f32_16x16x32_bf16 v[74:77], v[164:167], v[188:191], v[74:77]
	v_mfma_f32_16x16x32_bf16 v[70:73], v[156:159], v[196:199], v[70:73]
	v_mfma_f32_16x16x32_bf16 v[66:69], v[164:167], v[196:199], v[66:69]
	v_mfma_f32_16x16x32_bf16 v[112:115], v[160:163], v[176:179], v[112:115]
	v_mfma_f32_16x16x32_bf16 v[108:111], v[168:171], v[176:179], v[108:111]
	v_mfma_f32_16x16x32_bf16 v[94:97], v[160:163], v[184:187], v[94:97]
	v_mfma_f32_16x16x32_bf16 v[90:93], v[168:171], v[184:187], v[90:93]
	v_mfma_f32_16x16x32_bf16 v[78:81], v[160:163], v[192:195], v[78:81]
	v_mfma_f32_16x16x32_bf16 v[74:77], v[168:171], v[192:195], v[74:77]
	v_mfma_f32_16x16x32_bf16 v[70:73], v[160:163], v[214:217], v[70:73]
	v_mfma_f32_16x16x32_bf16 v[66:69], v[168:171], v[214:217], v[66:69]
	s_setprio 0
	s_barrier
	s_mov_b32 m0, s79
	v_lshl_add_u64 v[204:205], s[66:67], 0, v[98:99]
	ds_read_b128 v[172:175], v139 offset:16384
	ds_read_b128 v[176:179], v139 offset:17408
	ds_read_b128 v[180:183], v139 offset:18432
	ds_read_b128 v[184:187], v139 offset:19456
	ds_read_b128 v[188:191], v139 offset:20480
	ds_read_b128 v[192:195], v139 offset:21504
	ds_read_b128 v[196:199], v139 offset:22528
	ds_read_b128 v[214:217], v139 offset:23552
	s_setprio 1
	global_load_lds_dwordx4 v[204:205], off
	v_lshl_add_u64 v[206:207], s[66:67], 0, v[132:133]
	s_mov_b32 m0, s76
	v_lshl_add_u64 v[208:209], s[70:71], 0, v[98:99]
	global_load_lds_dwordx4 v[206:207], off
	s_mov_b32 m0, s78
	v_lshl_add_u64 v[210:211], s[64:65], 0, v[134:135]
	global_load_lds_dwordx4 v[208:209], off
	v_lshl_add_u64 v[208:209], s[70:71], 0, v[132:133]
	s_mov_b32 m0, s77
	s_nop 0
	global_load_lds_dwordx4 v[208:209], off
	v_lshl_add_u64 v[208:209], s[64:65], 0, v[136:137]
	s_mov_b32 m0, s4
	s_nop 0
	global_load_lds_dwordx4 v[208:209], off
	s_mov_b32 m0, s7
	s_nop 0
	global_load_lds_dwordx4 v[210:211], off
	s_waitcnt vmcnt(8) lgkmcnt(0)
	s_barrier
	v_mfma_f32_16x16x32_bf16 v[62:65], v[140:143], v[172:175], v[62:65]
	v_mfma_f32_16x16x32_bf16 v[58:61], v[148:151], v[172:175], v[58:61]
	v_mfma_f32_16x16x32_bf16 v[54:57], v[140:143], v[180:183], v[54:57]
	v_mfma_f32_16x16x32_bf16 v[50:53], v[148:151], v[180:183], v[50:53]
	v_mfma_f32_16x16x32_bf16 v[38:41], v[140:143], v[188:191], v[38:41]
	v_mfma_f32_16x16x32_bf16 v[34:37], v[148:151], v[188:191], v[34:37]
	v_mfma_f32_16x16x32_bf16 v[22:25], v[140:143], v[196:199], v[22:25]
	v_mfma_f32_16x16x32_bf16 v[18:21], v[148:151], v[196:199], v[18:21]
	v_mfma_f32_16x16x32_bf16 v[62:65], v[144:147], v[176:179], v[62:65]
	v_mfma_f32_16x16x32_bf16 v[58:61], v[152:155], v[176:179], v[58:61]
	v_mfma_f32_16x16x32_bf16 v[54:57], v[144:147], v[184:187], v[54:57]
	v_mfma_f32_16x16x32_bf16 v[50:53], v[152:155], v[184:187], v[50:53]
	v_mfma_f32_16x16x32_bf16 v[38:41], v[144:147], v[192:195], v[38:41]
	v_mfma_f32_16x16x32_bf16 v[34:37], v[152:155], v[192:195], v[34:37]
	v_mfma_f32_16x16x32_bf16 v[22:25], v[144:147], v[214:217], v[22:25]
	v_mfma_f32_16x16x32_bf16 v[18:21], v[152:155], v[214:217], v[18:21]
	s_setprio 0
	s_setprio 1
	v_mfma_f32_16x16x32_bf16 v[46:49], v[156:159], v[172:175], v[46:49]
	v_mfma_f32_16x16x32_bf16 v[42:45], v[164:167], v[172:175], v[42:45]
	v_mfma_f32_16x16x32_bf16 v[30:33], v[156:159], v[180:183], v[30:33]
	v_mfma_f32_16x16x32_bf16 v[26:29], v[164:167], v[180:183], v[26:29]
	v_mfma_f32_16x16x32_bf16 v[14:17], v[156:159], v[188:191], v[14:17]
	v_mfma_f32_16x16x32_bf16 v[10:13], v[164:167], v[188:191], v[10:13]
	v_mfma_f32_16x16x32_bf16 v[6:9], v[156:159], v[196:199], v[6:9]
	v_mfma_f32_16x16x32_bf16 v[2:5], v[164:167], v[196:199], v[2:5]
	v_mfma_f32_16x16x32_bf16 v[46:49], v[160:163], v[176:179], v[46:49]
	v_mfma_f32_16x16x32_bf16 v[42:45], v[168:171], v[176:179], v[42:45]
	v_mfma_f32_16x16x32_bf16 v[30:33], v[160:163], v[184:187], v[30:33]
	v_mfma_f32_16x16x32_bf16 v[26:29], v[168:171], v[184:187], v[26:29]
	v_mfma_f32_16x16x32_bf16 v[14:17], v[160:163], v[192:195], v[14:17]
	v_mfma_f32_16x16x32_bf16 v[10:13], v[168:171], v[192:195], v[10:13]
	v_mfma_f32_16x16x32_bf16 v[6:9], v[160:163], v[214:217], v[6:9]
	v_mfma_f32_16x16x32_bf16 v[2:5], v[168:171], v[214:217], v[2:5]
	s_setprio 0
	s_barrier
	v_add_u32_e32 v152, s75, v138
	v_add_u32_e32 v168, s74, v138
	ds_read_b128 v[140:143], v152
	ds_read_b128 v[144:147], v152 offset:1024
	ds_read_b128 v[148:151], v152 offset:2048
	ds_read_b128 v[152:155], v152 offset:3072
	ds_read_b128 v[156:159], v168
	ds_read_b128 v[160:163], v168 offset:1024
	ds_read_b128 v[164:167], v168 offset:2048
	ds_read_b128 v[168:171], v168 offset:3072
	s_mov_b32 m0, s8
	v_lshl_add_u64 v[218:219], s[62:63], 0, v[136:137]
	ds_read_b128 v[172:175], v139 offset:32768
	ds_read_b128 v[176:179], v139 offset:33792
	ds_read_b128 v[180:183], v139 offset:34816
	ds_read_b128 v[184:187], v139 offset:35840
	ds_read_b128 v[188:191], v139 offset:36864
	ds_read_b128 v[192:195], v139 offset:37888
	ds_read_b128 v[196:199], v139 offset:38912
	ds_read_b128 v[214:217], v139 offset:39936
	s_setprio 1
	global_load_lds_dwordx4 v[218:219], off
	v_lshl_add_u64 v[218:219], s[62:63], 0, v[134:135]
	s_mov_b32 m0, s9
	s_nop 0
	global_load_lds_dwordx4 v[218:219], off
	s_waitcnt vmcnt(8) lgkmcnt(0)
	s_barrier
	v_mfma_f32_16x16x32_bf16 v[128:131], v[140:143], v[172:175], v[128:131]
	v_mfma_f32_16x16x32_bf16 v[124:127], v[148:151], v[172:175], v[124:127]
	v_mfma_f32_16x16x32_bf16 v[120:123], v[140:143], v[180:183], v[120:123]
	v_mfma_f32_16x16x32_bf16 v[116:119], v[148:151], v[180:183], v[116:119]
	v_mfma_f32_16x16x32_bf16 v[104:107], v[140:143], v[188:191], v[104:107]
	v_mfma_f32_16x16x32_bf16 v[100:103], v[148:151], v[188:191], v[100:103]
	v_mfma_f32_16x16x32_bf16 v[86:89], v[140:143], v[196:199], v[86:89]
	v_mfma_f32_16x16x32_bf16 v[82:85], v[148:151], v[196:199], v[82:85]
	v_mfma_f32_16x16x32_bf16 v[128:131], v[144:147], v[176:179], v[128:131]
	v_mfma_f32_16x16x32_bf16 v[124:127], v[152:155], v[176:179], v[124:127]
	v_mfma_f32_16x16x32_bf16 v[120:123], v[144:147], v[184:187], v[120:123]
	v_mfma_f32_16x16x32_bf16 v[116:119], v[152:155], v[184:187], v[116:119]
	v_mfma_f32_16x16x32_bf16 v[104:107], v[144:147], v[192:195], v[104:107]
	v_mfma_f32_16x16x32_bf16 v[100:103], v[152:155], v[192:195], v[100:103]
	v_mfma_f32_16x16x32_bf16 v[86:89], v[144:147], v[214:217], v[86:89]
	v_mfma_f32_16x16x32_bf16 v[82:85], v[152:155], v[214:217], v[82:85]
	s_setprio 0
	s_setprio 1
	v_mfma_f32_16x16x32_bf16 v[112:115], v[156:159], v[172:175], v[112:115]
	v_mfma_f32_16x16x32_bf16 v[108:111], v[164:167], v[172:175], v[108:111]
	v_mfma_f32_16x16x32_bf16 v[94:97], v[156:159], v[180:183], v[94:97]
	v_mfma_f32_16x16x32_bf16 v[90:93], v[164:167], v[180:183], v[90:93]
	v_mfma_f32_16x16x32_bf16 v[78:81], v[156:159], v[188:191], v[78:81]
	v_mfma_f32_16x16x32_bf16 v[74:77], v[164:167], v[188:191], v[74:77]
	v_mfma_f32_16x16x32_bf16 v[70:73], v[156:159], v[196:199], v[70:73]
	v_mfma_f32_16x16x32_bf16 v[66:69], v[164:167], v[196:199], v[66:69]
	v_mfma_f32_16x16x32_bf16 v[112:115], v[160:163], v[176:179], v[112:115]
	v_mfma_f32_16x16x32_bf16 v[108:111], v[168:171], v[176:179], v[108:111]
	v_mfma_f32_16x16x32_bf16 v[94:97], v[160:163], v[184:187], v[94:97]
	v_mfma_f32_16x16x32_bf16 v[90:93], v[168:171], v[184:187], v[90:93]
	v_mfma_f32_16x16x32_bf16 v[78:81], v[160:163], v[192:195], v[78:81]
	v_mfma_f32_16x16x32_bf16 v[74:77], v[168:171], v[192:195], v[74:77]
	v_mfma_f32_16x16x32_bf16 v[70:73], v[160:163], v[214:217], v[70:73]
	v_mfma_f32_16x16x32_bf16 v[66:69], v[168:171], v[214:217], v[66:69]
	s_setprio 0
	s_barrier
	s_mov_b32 m0, s68
	v_lshl_add_u64 v[204:205], v[204:205], 0, s[28:29]
	ds_read_b128 v[172:175], v139 offset:49152
	ds_read_b128 v[176:179], v139 offset:50176
	ds_read_b128 v[180:183], v139 offset:51200
	ds_read_b128 v[184:187], v139 offset:52224
	ds_read_b128 v[188:191], v139 offset:53248
	ds_read_b128 v[192:195], v139 offset:54272
	ds_read_b128 v[196:199], v139 offset:55296
	ds_read_b128 v[214:217], v139 offset:56320
	s_setprio 1
	global_load_lds_dwordx4 v[204:205], off
	v_lshl_add_u64 v[204:205], v[206:207], 0, s[28:29]
	s_mov_b32 m0, s49
	s_nop 0
	global_load_lds_dwordx4 v[204:205], off
	v_lshl_add_u64 v[204:205], s[60:61], 0, v[98:99]
	s_mov_b32 m0, s81
	s_nop 0
	global_load_lds_dwordx4 v[204:205], off
	v_lshl_add_u64 v[204:205], s[60:61], 0, v[132:133]
	s_mov_b32 m0, s80
	s_nop 0
	global_load_lds_dwordx4 v[204:205], off
	v_lshl_add_u64 v[204:205], v[208:209], 0, s[28:29]
	s_mov_b32 m0, s10
	s_nop 0
	global_load_lds_dwordx4 v[204:205], off
	v_lshl_add_u64 v[204:205], v[210:211], 0, s[28:29]
	s_mov_b32 m0, s11
	s_nop 0
	global_load_lds_dwordx4 v[204:205], off
	s_waitcnt vmcnt(8) lgkmcnt(0)
	s_barrier
	v_mfma_f32_16x16x32_bf16 v[62:65], v[140:143], v[172:175], v[62:65]
	v_mfma_f32_16x16x32_bf16 v[58:61], v[148:151], v[172:175], v[58:61]
	v_mfma_f32_16x16x32_bf16 v[54:57], v[140:143], v[180:183], v[54:57]
	v_mfma_f32_16x16x32_bf16 v[50:53], v[148:151], v[180:183], v[50:53]
	v_mfma_f32_16x16x32_bf16 v[38:41], v[140:143], v[188:191], v[38:41]
	v_mfma_f32_16x16x32_bf16 v[34:37], v[148:151], v[188:191], v[34:37]
	v_mfma_f32_16x16x32_bf16 v[22:25], v[140:143], v[196:199], v[22:25]
	v_mfma_f32_16x16x32_bf16 v[18:21], v[148:151], v[196:199], v[18:21]
	v_mfma_f32_16x16x32_bf16 v[62:65], v[144:147], v[176:179], v[62:65]
	v_mfma_f32_16x16x32_bf16 v[58:61], v[152:155], v[176:179], v[58:61]
	v_mfma_f32_16x16x32_bf16 v[54:57], v[144:147], v[184:187], v[54:57]
	v_mfma_f32_16x16x32_bf16 v[50:53], v[152:155], v[184:187], v[50:53]
	v_mfma_f32_16x16x32_bf16 v[38:41], v[144:147], v[192:195], v[38:41]
	v_mfma_f32_16x16x32_bf16 v[34:37], v[152:155], v[192:195], v[34:37]
	v_mfma_f32_16x16x32_bf16 v[22:25], v[144:147], v[214:217], v[22:25]
	v_mfma_f32_16x16x32_bf16 v[18:21], v[152:155], v[214:217], v[18:21]
	s_setprio 0
	s_setprio 1
	v_mfma_f32_16x16x32_bf16 v[46:49], v[156:159], v[172:175], v[46:49]
	v_mfma_f32_16x16x32_bf16 v[42:45], v[164:167], v[172:175], v[42:45]
	v_mfma_f32_16x16x32_bf16 v[30:33], v[156:159], v[180:183], v[30:33]
	v_mfma_f32_16x16x32_bf16 v[26:29], v[164:167], v[180:183], v[26:29]
	v_mfma_f32_16x16x32_bf16 v[14:17], v[156:159], v[188:191], v[14:17]
	v_mfma_f32_16x16x32_bf16 v[10:13], v[164:167], v[188:191], v[10:13]
	v_mfma_f32_16x16x32_bf16 v[6:9], v[156:159], v[196:199], v[6:9]
	v_mfma_f32_16x16x32_bf16 v[2:5], v[164:167], v[196:199], v[2:5]
	v_mfma_f32_16x16x32_bf16 v[46:49], v[160:163], v[176:179], v[46:49]
	v_mfma_f32_16x16x32_bf16 v[42:45], v[168:171], v[176:179], v[42:45]
	v_mfma_f32_16x16x32_bf16 v[30:33], v[160:163], v[184:187], v[30:33]
	v_mfma_f32_16x16x32_bf16 v[26:29], v[168:171], v[184:187], v[26:29]
	v_mfma_f32_16x16x32_bf16 v[14:17], v[160:163], v[192:195], v[14:17]
	v_mfma_f32_16x16x32_bf16 v[10:13], v[168:171], v[192:195], v[10:13]
	v_mfma_f32_16x16x32_bf16 v[6:9], v[160:163], v[214:217], v[6:9]
	v_mfma_f32_16x16x32_bf16 v[2:5], v[168:171], v[214:217], v[2:5]
	s_setprio 0
	s_barrier
	s_movk_i32 s49, 0x100
	s_andn2_b64 vcc, exec, s[58:59]
	s_mov_b64 s[60:61], -1
	s_mov_b64 s[58:59], 0
	s_cbranch_vccz .LBB0_333
	s_and_b64 vcc, exec, s[40:41]
	s_cbranch_vccz .LBB0_336
	s_barrier

.LBB0_438:
	s_add_u32 s42, s40, 0xfffc0080
	s_addc_u32 s43, s41, -1
	s_add_i32 s67, 0, 0x10000
	s_cmp_eq_u32 s66, 12
	s_cselect_b32 s45, s1, s43
	s_cselect_b32 s44, s49, s42
	s_cselect_b32 s43, s55, s65
	s_cselect_b32 s42, s63, s64
	s_add_i32 s72, 0, 0x14000
	v_add_u32_e32 v108, s67, v162
	v_add_u32_e32 v160, s72, v162
	ds_read_b128 v[90:93], v108
	ds_read_b128 v[94:97], v108 offset:1024
	ds_read_b128 v[100:103], v108 offset:2048
	ds_read_b128 v[108:111], v108 offset:3072
	ds_read_b128 v[166:169], v160
	ds_read_b128 v[170:173], v160 offset:1024
	ds_read_b128 v[174:177], v160 offset:2048
	ds_read_b128 v[178:181], v160 offset:3072
	v_lshl_add_u64 v[160:161], s[40:41], 0, v[156:157]
	s_add_i32 m0, s8, 0xc000
	ds_read_b128 v[182:185], v163
	ds_read_b128 v[186:189], v163 offset:1024
	ds_read_b128 v[190:193], v163 offset:2048
	ds_read_b128 v[194:197], v163 offset:3072
	ds_read_b128 v[214:217], v163 offset:4096
	ds_read_b128 v[218:221], v163 offset:5120
	ds_read_b128 v[222:225], v163 offset:6144
	ds_read_b128 v[226:229], v163 offset:7168
	s_setprio 1
	global_load_lds_dwordx4 v[160:161], off
	v_lshl_add_u64 v[160:161], s[40:41], 0, v[158:159]
	s_add_i32 m0, s8, 0xe000
	s_nop 0
	global_load_lds_dwordx4 v[160:161], off
	s_waitcnt vmcnt(8) lgkmcnt(0)
	s_barrier
	v_mfma_f32_16x16x32_bf16 v[144:147], v[90:93], v[182:185], v[144:147]
	v_mfma_f32_16x16x32_bf16 v[140:143], v[100:103], v[182:185], v[140:143]
	v_mfma_f32_16x16x32_bf16 v[128:131], v[90:93], v[190:193], v[128:131]
	v_mfma_f32_16x16x32_bf16 v[124:127], v[100:103], v[190:193], v[124:127]
	v_mfma_f32_16x16x32_bf16 v[112:115], v[90:93], v[214:217], v[112:115]
	v_mfma_f32_16x16x32_bf16 v[104:107], v[100:103], v[214:217], v[104:107]
	v_mfma_f32_16x16x32_bf16 v[78:81], v[90:93], v[222:225], v[78:81]
	v_mfma_f32_16x16x32_bf16 v[74:77], v[100:103], v[222:225], v[74:77]
	v_mfma_f32_16x16x32_bf16 v[144:147], v[94:97], v[186:189], v[144:147]
	v_mfma_f32_16x16x32_bf16 v[140:143], v[108:111], v[186:189], v[140:143]
	v_mfma_f32_16x16x32_bf16 v[128:131], v[94:97], v[194:197], v[128:131]
	v_mfma_f32_16x16x32_bf16 v[124:127], v[108:111], v[194:197], v[124:127]
	v_mfma_f32_16x16x32_bf16 v[112:115], v[94:97], v[218:221], v[112:115]
	v_mfma_f32_16x16x32_bf16 v[104:107], v[108:111], v[218:221], v[104:107]
	v_mfma_f32_16x16x32_bf16 v[78:81], v[94:97], v[226:229], v[78:81]
	v_mfma_f32_16x16x32_bf16 v[74:77], v[108:111], v[226:229], v[74:77]
	s_setprio 0
	s_setprio 1
	v_mfma_f32_16x16x32_bf16 v[136:139], v[166:169], v[182:185], v[136:139]
	v_mfma_f32_16x16x32_bf16 v[132:135], v[174:177], v[182:185], v[132:135]
	v_mfma_f32_16x16x32_bf16 v[120:123], v[166:169], v[190:193], v[120:123]
	v_mfma_f32_16x16x32_bf16 v[116:119], v[174:177], v[190:193], v[116:119]
	v_mfma_f32_16x16x32_bf16 v[86:89], v[166:169], v[214:217], v[86:89]
	v_mfma_f32_16x16x32_bf16 v[82:85], v[174:177], v[214:217], v[82:85]
	v_mfma_f32_16x16x32_bf16 v[70:73], v[166:169], v[222:225], v[70:73]
	v_mfma_f32_16x16x32_bf16 v[66:69], v[174:177], v[222:225], v[66:69]
	v_mfma_f32_16x16x32_bf16 v[136:139], v[170:173], v[186:189], v[136:139]
	v_mfma_f32_16x16x32_bf16 v[132:135], v[178:181], v[186:189], v[132:135]
	v_mfma_f32_16x16x32_bf16 v[120:123], v[170:173], v[194:197], v[120:123]
	v_mfma_f32_16x16x32_bf16 v[116:119], v[178:181], v[194:197], v[116:119]
	v_mfma_f32_16x16x32_bf16 v[86:89], v[170:173], v[218:221], v[86:89]
	v_mfma_f32_16x16x32_bf16 v[82:85], v[178:181], v[218:221], v[82:85]
	v_mfma_f32_16x16x32_bf16 v[70:73], v[170:173], v[226:229], v[70:73]
	v_mfma_f32_16x16x32_bf16 v[66:69], v[178:181], v[226:229], v[66:69]
	s_setprio 0
	s_barrier
	s_add_i32 s67, s67, s7
	v_lshl_add_u64 v[160:161], s[42:43], 0, v[98:99]
	s_mov_b32 m0, s67
	ds_read_b128 v[182:185], v163 offset:16384
	ds_read_b128 v[186:189], v163 offset:17408
	ds_read_b128 v[190:193], v163 offset:18432
	ds_read_b128 v[194:197], v163 offset:19456
	ds_read_b128 v[214:217], v163 offset:20480
	ds_read_b128 v[218:221], v163 offset:21504
	ds_read_b128 v[222:225], v163 offset:22528
	ds_read_b128 v[226:229], v163 offset:23552
	s_setprio 1
	global_load_lds_dwordx4 v[160:161], off
	s_add_i32 m0, s67, 0x2000
	s_add_u32 s70, s42, 0x40000
	v_lshl_add_u64 v[198:199], s[42:43], 0, v[152:153]
	s_addc_u32 s71, s43, 0
	s_add_i32 s67, s72, s7
	global_load_lds_dwordx4 v[198:199], off
	v_lshl_add_u64 v[204:205], s[70:71], 0, v[98:99]
	s_mov_b32 m0, s67
	v_lshl_add_u64 v[206:207], s[44:45], 0, v[150:151]
	global_load_lds_dwordx4 v[204:205], off
	v_lshl_add_u64 v[204:205], s[70:71], 0, v[152:153]
	s_add_i32 m0, s67, 0x2000
	s_nop 0
	global_load_lds_dwordx4 v[204:205], off
	v_lshl_add_u64 v[204:205], s[44:45], 0, v[148:149]
	s_mov_b32 m0, s8
	s_nop 0
	global_load_lds_dwordx4 v[204:205], off
	s_mov_b32 m0, s9
	s_nop 0
	global_load_lds_dwordx4 v[206:207], off
	s_waitcnt vmcnt(8) lgkmcnt(0)
	s_barrier
	v_mfma_f32_16x16x32_bf16 v[62:65], v[90:93], v[182:185], v[62:65]
	v_mfma_f32_16x16x32_bf16 v[58:61], v[100:103], v[182:185], v[58:61]
	v_mfma_f32_16x16x32_bf16 v[46:49], v[90:93], v[190:193], v[46:49]
	v_mfma_f32_16x16x32_bf16 v[42:45], v[100:103], v[190:193], v[42:45]
	v_mfma_f32_16x16x32_bf16 v[30:33], v[90:93], v[214:217], v[30:33]
	v_mfma_f32_16x16x32_bf16 v[26:29], v[100:103], v[214:217], v[26:29]
	v_mfma_f32_16x16x32_bf16 v[14:17], v[90:93], v[222:225], v[14:17]
	v_mfma_f32_16x16x32_bf16 v[10:13], v[100:103], v[222:225], v[10:13]
	v_mfma_f32_16x16x32_bf16 v[62:65], v[94:97], v[186:189], v[62:65]
	v_mfma_f32_16x16x32_bf16 v[58:61], v[108:111], v[186:189], v[58:61]
	v_mfma_f32_16x16x32_bf16 v[46:49], v[94:97], v[194:197], v[46:49]
	v_mfma_f32_16x16x32_bf16 v[42:45], v[108:111], v[194:197], v[42:45]
	v_mfma_f32_16x16x32_bf16 v[30:33], v[94:97], v[218:221], v[30:33]
	v_mfma_f32_16x16x32_bf16 v[26:29], v[108:111], v[218:221], v[26:29]
	v_mfma_f32_16x16x32_bf16 v[14:17], v[94:97], v[226:229], v[14:17]
	v_mfma_f32_16x16x32_bf16 v[10:13], v[108:111], v[226:229], v[10:13]
	s_setprio 0
	s_setprio 1
	v_mfma_f32_16x16x32_bf16 v[54:57], v[166:169], v[182:185], v[54:57]
	v_mfma_f32_16x16x32_bf16 v[50:53], v[174:177], v[182:185], v[50:53]
	v_mfma_f32_16x16x32_bf16 v[38:41], v[166:169], v[190:193], v[38:41]
	v_mfma_f32_16x16x32_bf16 v[34:37], v[174:177], v[190:193], v[34:37]
	v_mfma_f32_16x16x32_bf16 v[22:25], v[166:169], v[214:217], v[22:25]
	v_mfma_f32_16x16x32_bf16 v[18:21], v[174:177], v[214:217], v[18:21]
	v_mfma_f32_16x16x32_bf16 v[6:9], v[166:169], v[222:225], v[6:9]
	v_mfma_f32_16x16x32_bf16 v[2:5], v[174:177], v[222:225], v[2:5]
	v_mfma_f32_16x16x32_bf16 v[54:57], v[170:173], v[186:189], v[54:57]
	v_mfma_f32_16x16x32_bf16 v[50:53], v[178:181], v[186:189], v[50:53]
	v_mfma_f32_16x16x32_bf16 v[38:41], v[170:173], v[194:197], v[38:41]
	v_mfma_f32_16x16x32_bf16 v[34:37], v[178:181], v[194:197], v[34:37]
	v_mfma_f32_16x16x32_bf16 v[22:25], v[170:173], v[218:221], v[22:25]
	v_mfma_f32_16x16x32_bf16 v[18:21], v[178:181], v[218:221], v[18:21]
	v_mfma_f32_16x16x32_bf16 v[6:9], v[170:173], v[226:229], v[6:9]
	v_mfma_f32_16x16x32_bf16 v[2:5], v[178:181], v[226:229], v[2:5]
	s_setprio 0
	s_barrier
	s_add_i32 s67, 0, 0x18000
	s_add_i32 s70, 0, 0x1c000
	v_add_u32_e32 v108, s67, v162
	v_add_u32_e32 v165, s70, v162
	ds_read_b128 v[90:93], v108
	ds_read_b128 v[94:97], v108 offset:1024
	ds_read_b128 v[100:103], v108 offset:2048
	ds_read_b128 v[108:111], v108 offset:3072
	ds_read_b128 v[166:169], v165
	ds_read_b128 v[170:173], v165 offset:1024
	ds_read_b128 v[174:177], v165 offset:2048
	ds_read_b128 v[178:181], v165 offset:3072
	s_add_u32 s44, s44, 0x40000
	s_addc_u32 s45, s45, 0
	s_mov_b32 m0, s10
	v_lshl_add_u64 v[208:209], s[44:45], 0, v[148:149]
	ds_read_b128 v[182:185], v163 offset:32768
	ds_read_b128 v[186:189], v163 offset:33792
	ds_read_b128 v[190:193], v163 offset:34816
	ds_read_b128 v[194:197], v163 offset:35840
	ds_read_b128 v[214:217], v163 offset:36864
	ds_read_b128 v[218:221], v163 offset:37888
	ds_read_b128 v[222:225], v163 offset:38912
	ds_read_b128 v[226:229], v163 offset:39936
	s_setprio 1
	global_load_lds_dwordx4 v[208:209], off
	v_lshl_add_u64 v[208:209], s[44:45], 0, v[150:151]
	s_mov_b32 m0, s11
	s_nop 0
	global_load_lds_dwordx4 v[208:209], off
	s_waitcnt vmcnt(8) lgkmcnt(0)
	s_barrier
	v_mfma_f32_16x16x32_bf16 v[144:147], v[90:93], v[182:185], v[144:147]
	v_mfma_f32_16x16x32_bf16 v[140:143], v[100:103], v[182:185], v[140:143]
	v_mfma_f32_16x16x32_bf16 v[128:131], v[90:93], v[190:193], v[128:131]
	v_mfma_f32_16x16x32_bf16 v[124:127], v[100:103], v[190:193], v[124:127]
	v_mfma_f32_16x16x32_bf16 v[112:115], v[90:93], v[214:217], v[112:115]
	v_mfma_f32_16x16x32_bf16 v[104:107], v[100:103], v[214:217], v[104:107]
	v_mfma_f32_16x16x32_bf16 v[78:81], v[90:93], v[222:225], v[78:81]
	v_mfma_f32_16x16x32_bf16 v[74:77], v[100:103], v[222:225], v[74:77]
	v_mfma_f32_16x16x32_bf16 v[144:147], v[94:97], v[186:189], v[144:147]
	v_mfma_f32_16x16x32_bf16 v[140:143], v[108:111], v[186:189], v[140:143]
	v_mfma_f32_16x16x32_bf16 v[128:131], v[94:97], v[194:197], v[128:131]
	v_mfma_f32_16x16x32_bf16 v[124:127], v[108:111], v[194:197], v[124:127]
	v_mfma_f32_16x16x32_bf16 v[112:115], v[94:97], v[218:221], v[112:115]
	v_mfma_f32_16x16x32_bf16 v[104:107], v[108:111], v[218:221], v[104:107]
	v_mfma_f32_16x16x32_bf16 v[78:81], v[94:97], v[226:229], v[78:81]
	v_mfma_f32_16x16x32_bf16 v[74:77], v[108:111], v[226:229], v[74:77]
	s_setprio 0
	s_setprio 1
	v_mfma_f32_16x16x32_bf16 v[136:139], v[166:169], v[182:185], v[136:139]
	v_mfma_f32_16x16x32_bf16 v[132:135], v[174:177], v[182:185], v[132:135]
	v_mfma_f32_16x16x32_bf16 v[120:123], v[166:169], v[190:193], v[120:123]
	v_mfma_f32_16x16x32_bf16 v[116:119], v[174:177], v[190:193], v[116:119]
	v_mfma_f32_16x16x32_bf16 v[86:89], v[166:169], v[214:217], v[86:89]
	v_mfma_f32_16x16x32_bf16 v[82:85], v[174:177], v[214:217], v[82:85]
	v_mfma_f32_16x16x32_bf16 v[70:73], v[166:169], v[222:225], v[70:73]
	v_mfma_f32_16x16x32_bf16 v[66:69], v[174:177], v[222:225], v[66:69]
	v_mfma_f32_16x16x32_bf16 v[136:139], v[170:173], v[186:189], v[136:139]
	v_mfma_f32_16x16x32_bf16 v[132:135], v[178:181], v[186:189], v[132:135]
	v_mfma_f32_16x16x32_bf16 v[120:123], v[170:173], v[194:197], v[120:123]
	v_mfma_f32_16x16x32_bf16 v[116:119], v[178:181], v[194:197], v[116:119]
	v_mfma_f32_16x16x32_bf16 v[86:89], v[170:173], v[218:221], v[86:89]
	v_mfma_f32_16x16x32_bf16 v[82:85], v[178:181], v[218:221], v[82:85]
	v_mfma_f32_16x16x32_bf16 v[70:73], v[170:173], v[226:229], v[70:73]
	v_mfma_f32_16x16x32_bf16 v[66:69], v[178:181], v[226:229], v[66:69]
	s_setprio 0
	s_barrier
	s_add_i32 s44, s67, s7
	v_lshl_add_u64 v[160:161], v[160:161], 0, s[28:29]
	s_mov_b32 m0, s44
	ds_read_b128 v[182:185], v163 offset:49152
	ds_read_b128 v[186:189], v163 offset:50176
	ds_read_b128 v[190:193], v163 offset:51200
	ds_read_b128 v[194:197], v163 offset:52224
	ds_read_b128 v[214:217], v163 offset:53248
	ds_read_b128 v[218:221], v163 offset:54272
	ds_read_b128 v[222:225], v163 offset:55296
	ds_read_b128 v[226:229], v163 offset:56320
	s_setprio 1
	global_load_lds_dwordx4 v[160:161], off
	s_add_i32 m0, s44, 0x2000
	s_add_u32 s42, s42, 0x40080
	v_lshl_add_u64 v[160:161], v[198:199], 0, s[28:29]
	s_addc_u32 s43, s43, 0
	s_add_i32 s44, s70, s7
	global_load_lds_dwordx4 v[160:161], off
	v_lshl_add_u64 v[160:161], s[42:43], 0, v[98:99]
	s_mov_b32 m0, s44
	s_nop 0
	global_load_lds_dwordx4 v[160:161], off
	v_lshl_add_u64 v[160:161], s[42:43], 0, v[152:153]
	s_add_i32 m0, s44, 0x2000
	s_nop 0
	global_load_lds_dwordx4 v[160:161], off
	v_lshl_add_u64 v[160:161], v[204:205], 0, s[28:29]
	s_mov_b32 m0, s16
	s_nop 0
	global_load_lds_dwordx4 v[160:161], off
	v_lshl_add_u64 v[160:161], v[206:207], 0, s[28:29]
	s_mov_b32 m0, s17
	s_nop 0
	global_load_lds_dwordx4 v[160:161], off
	s_waitcnt vmcnt(8) lgkmcnt(0)
	s_barrier
	v_mfma_f32_16x16x32_bf16 v[62:65], v[90:93], v[182:185], v[62:65]
	v_mfma_f32_16x16x32_bf16 v[58:61], v[100:103], v[182:185], v[58:61]
	v_mfma_f32_16x16x32_bf16 v[46:49], v[90:93], v[190:193], v[46:49]
	v_mfma_f32_16x16x32_bf16 v[42:45], v[100:103], v[190:193], v[42:45]
	v_mfma_f32_16x16x32_bf16 v[30:33], v[90:93], v[214:217], v[30:33]
	v_mfma_f32_16x16x32_bf16 v[26:29], v[100:103], v[214:217], v[26:29]
	v_mfma_f32_16x16x32_bf16 v[14:17], v[90:93], v[222:225], v[14:17]
	v_mfma_f32_16x16x32_bf16 v[10:13], v[100:103], v[222:225], v[10:13]
	v_mfma_f32_16x16x32_bf16 v[62:65], v[94:97], v[186:189], v[62:65]
	v_mfma_f32_16x16x32_bf16 v[58:61], v[108:111], v[186:189], v[58:61]
	v_mfma_f32_16x16x32_bf16 v[46:49], v[94:97], v[194:197], v[46:49]
	v_mfma_f32_16x16x32_bf16 v[42:45], v[108:111], v[194:197], v[42:45]
	v_mfma_f32_16x16x32_bf16 v[30:33], v[94:97], v[218:221], v[30:33]
	v_mfma_f32_16x16x32_bf16 v[26:29], v[108:111], v[218:221], v[26:29]
	v_mfma_f32_16x16x32_bf16 v[14:17], v[94:97], v[226:229], v[14:17]
	v_mfma_f32_16x16x32_bf16 v[10:13], v[108:111], v[226:229], v[10:13]
	s_setprio 0
	s_setprio 1
	v_mfma_f32_16x16x32_bf16 v[54:57], v[166:169], v[182:185], v[54:57]
	v_mfma_f32_16x16x32_bf16 v[50:53], v[174:177], v[182:185], v[50:53]
	v_mfma_f32_16x16x32_bf16 v[38:41], v[166:169], v[190:193], v[38:41]
	v_mfma_f32_16x16x32_bf16 v[34:37], v[174:177], v[190:193], v[34:37]
	v_mfma_f32_16x16x32_bf16 v[22:25], v[166:169], v[214:217], v[22:25]
	v_mfma_f32_16x16x32_bf16 v[18:21], v[174:177], v[214:217], v[18:21]
	v_mfma_f32_16x16x32_bf16 v[6:9], v[166:169], v[222:225], v[6:9]
	v_mfma_f32_16x16x32_bf16 v[2:5], v[174:177], v[222:225], v[2:5]
	v_mfma_f32_16x16x32_bf16 v[54:57], v[170:173], v[186:189], v[54:57]
	v_mfma_f32_16x16x32_bf16 v[50:53], v[178:181], v[186:189], v[50:53]
	v_mfma_f32_16x16x32_bf16 v[38:41], v[170:173], v[194:197], v[38:41]
	v_mfma_f32_16x16x32_bf16 v[34:37], v[178:181], v[194:197], v[34:37]
	v_mfma_f32_16x16x32_bf16 v[22:25], v[170:173], v[218:221], v[22:25]
	v_mfma_f32_16x16x32_bf16 v[18:21], v[178:181], v[218:221], v[18:21]
	v_mfma_f32_16x16x32_bf16 v[6:9], v[170:173], v[226:229], v[6:9]
	v_mfma_f32_16x16x32_bf16 v[2:5], v[178:181], v[226:229], v[2:5]
	s_setprio 0
	s_barrier
	s_add_i32 s66, s66, 2
	s_add_u32 s40, s40, 0x100
	s_addc_u32 s41, s41, 0
	s_add_u32 s64, s64, 0x100
	s_addc_u32 s65, s65, 0
	s_cmp_gt_u32 s66, 13
	s_cbranch_scc0 .LBB0_438
	s_and_b64 vcc, exec, s[22:23]
	s_cbranch_vccz .LBB0_441
	s_barrier

.LBB0_647:
	s_add_i32 s68, s42, 2
	s_add_u32 s43, s40, 0xfff80080
	s_addc_u32 s54, s41, -1
	s_add_i32 s70, 0, 0x10000
	s_cmp_eq_u32 s65, s42
	s_cselect_b32 s55, s49, s54
	s_cselect_b32 s54, s63, s43
	v_add_u32_e32 v146, s70, v149
	s_cselect_b32 s43, s51, s67
	s_cselect_b32 s42, s50, s66
	s_add_i32 s72, 0, 0x14000
	ds_read_b128 v[152:155], v146
	ds_read_b128 v[156:159], v146 offset:1024
	ds_read_b128 v[160:163], v146 offset:2048
	ds_read_b128 v[164:167], v146 offset:3072
	v_add_u32_e32 v146, s72, v149
	ds_read_b128 v[168:171], v146
	ds_read_b128 v[172:175], v146 offset:1024
	ds_read_b128 v[176:179], v146 offset:2048
	ds_read_b128 v[180:183], v146 offset:3072
	v_lshl_add_u64 v[146:147], s[40:41], 0, v[142:143]
	s_add_i32 m0, s11, 0xc000
	ds_read_b128 v[184:187], v150
	ds_read_b128 v[188:191], v150 offset:1024
	ds_read_b128 v[192:195], v150 offset:2048
	ds_read_b128 v[196:199], v150 offset:3072
	ds_read_b128 v[214:217], v150 offset:4096
	ds_read_b128 v[218:221], v150 offset:5120
	ds_read_b128 v[222:225], v150 offset:6144
	ds_read_b128 v[226:229], v150 offset:7168
	s_setprio 1
	global_load_lds_dwordx4 v[146:147], off
	v_lshl_add_u64 v[146:147], s[40:41], 0, v[144:145]
	s_add_i32 m0, s11, 0xe000
	s_nop 0
	global_load_lds_dwordx4 v[146:147], off
	s_waitcnt vmcnt(8) lgkmcnt(0)
	s_barrier
	v_mfma_f32_16x16x32_bf16 v[128:131], v[152:155], v[184:187], v[128:131]
	v_mfma_f32_16x16x32_bf16 v[124:127], v[160:163], v[184:187], v[124:127]
	v_mfma_f32_16x16x32_bf16 v[112:115], v[152:155], v[192:195], v[112:115]
	v_mfma_f32_16x16x32_bf16 v[108:111], v[160:163], v[192:195], v[108:111]
	v_mfma_f32_16x16x32_bf16 v[94:97], v[152:155], v[214:217], v[94:97]
	v_mfma_f32_16x16x32_bf16 v[90:93], v[160:163], v[214:217], v[90:93]
	v_mfma_f32_16x16x32_bf16 v[78:81], v[152:155], v[222:225], v[78:81]
	v_mfma_f32_16x16x32_bf16 v[74:77], v[160:163], v[222:225], v[74:77]
	v_mfma_f32_16x16x32_bf16 v[128:131], v[156:159], v[188:191], v[128:131]
	v_mfma_f32_16x16x32_bf16 v[124:127], v[164:167], v[188:191], v[124:127]
	v_mfma_f32_16x16x32_bf16 v[112:115], v[156:159], v[196:199], v[112:115]
	v_mfma_f32_16x16x32_bf16 v[108:111], v[164:167], v[196:199], v[108:111]
	v_mfma_f32_16x16x32_bf16 v[94:97], v[156:159], v[218:221], v[94:97]
	v_mfma_f32_16x16x32_bf16 v[90:93], v[164:167], v[218:221], v[90:93]
	v_mfma_f32_16x16x32_bf16 v[78:81], v[156:159], v[226:229], v[78:81]
	v_mfma_f32_16x16x32_bf16 v[74:77], v[164:167], v[226:229], v[74:77]
	s_setprio 0
	s_setprio 1
	v_mfma_f32_16x16x32_bf16 v[120:123], v[168:171], v[184:187], v[120:123]
	v_mfma_f32_16x16x32_bf16 v[116:119], v[176:179], v[184:187], v[116:119]
	v_mfma_f32_16x16x32_bf16 v[104:107], v[168:171], v[192:195], v[104:107]
	v_mfma_f32_16x16x32_bf16 v[100:103], v[176:179], v[192:195], v[100:103]
	v_mfma_f32_16x16x32_bf16 v[86:89], v[168:171], v[214:217], v[86:89]
	v_mfma_f32_16x16x32_bf16 v[82:85], v[176:179], v[214:217], v[82:85]
	v_mfma_f32_16x16x32_bf16 v[70:73], v[168:171], v[222:225], v[70:73]
	v_mfma_f32_16x16x32_bf16 v[66:69], v[176:179], v[222:225], v[66:69]
	v_mfma_f32_16x16x32_bf16 v[120:123], v[172:175], v[188:191], v[120:123]
	v_mfma_f32_16x16x32_bf16 v[116:119], v[180:183], v[188:191], v[116:119]
	v_mfma_f32_16x16x32_bf16 v[104:107], v[172:175], v[196:199], v[104:107]
	v_mfma_f32_16x16x32_bf16 v[100:103], v[180:183], v[196:199], v[100:103]
	v_mfma_f32_16x16x32_bf16 v[86:89], v[172:175], v[218:221], v[86:89]
	v_mfma_f32_16x16x32_bf16 v[82:85], v[180:183], v[218:221], v[82:85]
	v_mfma_f32_16x16x32_bf16 v[70:73], v[172:175], v[226:229], v[70:73]
	v_mfma_f32_16x16x32_bf16 v[66:69], v[180:183], v[226:229], v[66:69]
	s_setprio 0
	s_barrier
	s_add_i32 s70, s70, s10
	v_lshl_add_u64 v[146:147], s[42:43], 0, v[98:99]
	s_mov_b32 m0, s70
	ds_read_b128 v[184:187], v150 offset:16384
	ds_read_b128 v[188:191], v150 offset:17408
	ds_read_b128 v[192:195], v150 offset:18432
	ds_read_b128 v[196:199], v150 offset:19456
	ds_read_b128 v[214:217], v150 offset:20480
	ds_read_b128 v[218:221], v150 offset:21504
	ds_read_b128 v[222:225], v150 offset:22528
	ds_read_b128 v[226:229], v150 offset:23552
	s_setprio 1
	global_load_lds_dwordx4 v[146:147], off
	s_add_i32 m0, s70, 0x2000
	s_add_u32 s70, s42, 0x18000
	v_lshl_add_u64 v[204:205], s[42:43], 0, v[136:137]
	s_addc_u32 s71, s43, 0
	s_add_i32 s72, s72, s10
	global_load_lds_dwordx4 v[204:205], off
	v_lshl_add_u64 v[206:207], s[70:71], 0, v[98:99]
	s_mov_b32 m0, s72
	v_lshl_add_u64 v[208:209], s[54:55], 0, v[134:135]
	global_load_lds_dwordx4 v[206:207], off
	v_lshl_add_u64 v[206:207], s[70:71], 0, v[136:137]
	s_add_i32 m0, s72, 0x2000
	s_nop 0
	global_load_lds_dwordx4 v[206:207], off
	v_lshl_add_u64 v[206:207], s[54:55], 0, v[132:133]
	s_mov_b32 m0, s11
	s_nop 0
	global_load_lds_dwordx4 v[206:207], off
	s_mov_b32 m0, s12
	s_nop 0
	global_load_lds_dwordx4 v[208:209], off
	s_waitcnt vmcnt(8) lgkmcnt(0)
	s_barrier
	v_mfma_f32_16x16x32_bf16 v[62:65], v[152:155], v[184:187], v[62:65]
	v_mfma_f32_16x16x32_bf16 v[58:61], v[160:163], v[184:187], v[58:61]
	v_mfma_f32_16x16x32_bf16 v[46:49], v[152:155], v[192:195], v[46:49]
	v_mfma_f32_16x16x32_bf16 v[42:45], v[160:163], v[192:195], v[42:45]
	v_mfma_f32_16x16x32_bf16 v[30:33], v[152:155], v[214:217], v[30:33]
	v_mfma_f32_16x16x32_bf16 v[26:29], v[160:163], v[214:217], v[26:29]
	v_mfma_f32_16x16x32_bf16 v[14:17], v[152:155], v[222:225], v[14:17]
	v_mfma_f32_16x16x32_bf16 v[10:13], v[160:163], v[222:225], v[10:13]
	v_mfma_f32_16x16x32_bf16 v[62:65], v[156:159], v[188:191], v[62:65]
	v_mfma_f32_16x16x32_bf16 v[58:61], v[164:167], v[188:191], v[58:61]
	v_mfma_f32_16x16x32_bf16 v[46:49], v[156:159], v[196:199], v[46:49]
	v_mfma_f32_16x16x32_bf16 v[42:45], v[164:167], v[196:199], v[42:45]
	v_mfma_f32_16x16x32_bf16 v[30:33], v[156:159], v[218:221], v[30:33]
	v_mfma_f32_16x16x32_bf16 v[26:29], v[164:167], v[218:221], v[26:29]
	v_mfma_f32_16x16x32_bf16 v[14:17], v[156:159], v[226:229], v[14:17]
	v_mfma_f32_16x16x32_bf16 v[10:13], v[164:167], v[226:229], v[10:13]
	s_setprio 0
	s_setprio 1
	v_mfma_f32_16x16x32_bf16 v[54:57], v[168:171], v[184:187], v[54:57]
	v_mfma_f32_16x16x32_bf16 v[50:53], v[176:179], v[184:187], v[50:53]
	v_mfma_f32_16x16x32_bf16 v[38:41], v[168:171], v[192:195], v[38:41]
	v_mfma_f32_16x16x32_bf16 v[34:37], v[176:179], v[192:195], v[34:37]
	v_mfma_f32_16x16x32_bf16 v[22:25], v[168:171], v[214:217], v[22:25]
	v_mfma_f32_16x16x32_bf16 v[18:21], v[176:179], v[214:217], v[18:21]
	v_mfma_f32_16x16x32_bf16 v[6:9], v[168:171], v[222:225], v[6:9]
	v_mfma_f32_16x16x32_bf16 v[2:5], v[176:179], v[222:225], v[2:5]
	v_mfma_f32_16x16x32_bf16 v[54:57], v[172:175], v[188:191], v[54:57]
	v_mfma_f32_16x16x32_bf16 v[50:53], v[180:183], v[188:191], v[50:53]
	v_mfma_f32_16x16x32_bf16 v[38:41], v[172:175], v[196:199], v[38:41]
	v_mfma_f32_16x16x32_bf16 v[34:37], v[180:183], v[196:199], v[34:37]
	v_mfma_f32_16x16x32_bf16 v[22:25], v[172:175], v[218:221], v[22:25]
	v_mfma_f32_16x16x32_bf16 v[18:21], v[180:183], v[218:221], v[18:21]
	v_mfma_f32_16x16x32_bf16 v[6:9], v[172:175], v[226:229], v[6:9]
	v_mfma_f32_16x16x32_bf16 v[2:5], v[180:183], v[226:229], v[2:5]
	s_setprio 0
	s_barrier
	s_add_i32 s70, 0, 0x18000
	v_add_u32_e32 v151, s70, v149
	s_add_i32 s71, 0, 0x1c000
	ds_read_b128 v[152:155], v151
	ds_read_b128 v[156:159], v151 offset:1024
	ds_read_b128 v[160:163], v151 offset:2048
	ds_read_b128 v[164:167], v151 offset:3072
	v_add_u32_e32 v151, s71, v149
	ds_read_b128 v[168:171], v151
	ds_read_b128 v[172:175], v151 offset:1024
	ds_read_b128 v[176:179], v151 offset:2048
	ds_read_b128 v[180:183], v151 offset:3072
	s_add_u32 s54, s54, 0x80000
	s_addc_u32 s55, s55, 0
	s_mov_b32 m0, s13
	v_lshl_add_u64 v[210:211], s[54:55], 0, v[132:133]
	ds_read_b128 v[184:187], v150 offset:32768
	ds_read_b128 v[188:191], v150 offset:33792
	ds_read_b128 v[192:195], v150 offset:34816
	ds_read_b128 v[196:199], v150 offset:35840
	ds_read_b128 v[214:217], v150 offset:36864
	ds_read_b128 v[218:221], v150 offset:37888
	ds_read_b128 v[222:225], v150 offset:38912
	ds_read_b128 v[226:229], v150 offset:39936
	s_setprio 1
	global_load_lds_dwordx4 v[210:211], off
	v_lshl_add_u64 v[210:211], s[54:55], 0, v[134:135]
	s_mov_b32 m0, s14
	s_nop 0
	global_load_lds_dwordx4 v[210:211], off
	s_waitcnt vmcnt(8) lgkmcnt(0)
	s_barrier
	v_mfma_f32_16x16x32_bf16 v[128:131], v[152:155], v[184:187], v[128:131]
	v_mfma_f32_16x16x32_bf16 v[124:127], v[160:163], v[184:187], v[124:127]
	v_mfma_f32_16x16x32_bf16 v[112:115], v[152:155], v[192:195], v[112:115]
	v_mfma_f32_16x16x32_bf16 v[108:111], v[160:163], v[192:195], v[108:111]
	v_mfma_f32_16x16x32_bf16 v[94:97], v[152:155], v[214:217], v[94:97]
	v_mfma_f32_16x16x32_bf16 v[90:93], v[160:163], v[214:217], v[90:93]
	v_mfma_f32_16x16x32_bf16 v[78:81], v[152:155], v[222:225], v[78:81]
	v_mfma_f32_16x16x32_bf16 v[74:77], v[160:163], v[222:225], v[74:77]
	v_mfma_f32_16x16x32_bf16 v[128:131], v[156:159], v[188:191], v[128:131]
	v_mfma_f32_16x16x32_bf16 v[124:127], v[164:167], v[188:191], v[124:127]
	v_mfma_f32_16x16x32_bf16 v[112:115], v[156:159], v[196:199], v[112:115]
	v_mfma_f32_16x16x32_bf16 v[108:111], v[164:167], v[196:199], v[108:111]
	v_mfma_f32_16x16x32_bf16 v[94:97], v[156:159], v[218:221], v[94:97]
	v_mfma_f32_16x16x32_bf16 v[90:93], v[164:167], v[218:221], v[90:93]
	v_mfma_f32_16x16x32_bf16 v[78:81], v[156:159], v[226:229], v[78:81]
	v_mfma_f32_16x16x32_bf16 v[74:77], v[164:167], v[226:229], v[74:77]
	s_setprio 0
	s_setprio 1
	v_mfma_f32_16x16x32_bf16 v[120:123], v[168:171], v[184:187], v[120:123]
	v_mfma_f32_16x16x32_bf16 v[116:119], v[176:179], v[184:187], v[116:119]
	v_mfma_f32_16x16x32_bf16 v[104:107], v[168:171], v[192:195], v[104:107]
	v_mfma_f32_16x16x32_bf16 v[100:103], v[176:179], v[192:195], v[100:103]
	v_mfma_f32_16x16x32_bf16 v[86:89], v[168:171], v[214:217], v[86:89]
	v_mfma_f32_16x16x32_bf16 v[82:85], v[176:179], v[214:217], v[82:85]
	v_mfma_f32_16x16x32_bf16 v[70:73], v[168:171], v[222:225], v[70:73]
	v_mfma_f32_16x16x32_bf16 v[66:69], v[176:179], v[222:225], v[66:69]
	v_mfma_f32_16x16x32_bf16 v[120:123], v[172:175], v[188:191], v[120:123]
	v_mfma_f32_16x16x32_bf16 v[116:119], v[180:183], v[188:191], v[116:119]
	v_mfma_f32_16x16x32_bf16 v[104:107], v[172:175], v[196:199], v[104:107]
	v_mfma_f32_16x16x32_bf16 v[100:103], v[180:183], v[196:199], v[100:103]
	v_mfma_f32_16x16x32_bf16 v[86:89], v[172:175], v[218:221], v[86:89]
	v_mfma_f32_16x16x32_bf16 v[82:85], v[180:183], v[218:221], v[82:85]
	v_mfma_f32_16x16x32_bf16 v[70:73], v[172:175], v[226:229], v[70:73]
	v_mfma_f32_16x16x32_bf16 v[66:69], v[180:183], v[226:229], v[66:69]
	s_setprio 0
	s_barrier
	s_add_i32 s54, s70, s10
	v_lshl_add_u64 v[146:147], v[146:147], 0, s[28:29]
	s_mov_b32 m0, s54
	ds_read_b128 v[184:187], v150 offset:49152
	ds_read_b128 v[188:191], v150 offset:50176
	ds_read_b128 v[192:195], v150 offset:51200
	ds_read_b128 v[196:199], v150 offset:52224
	ds_read_b128 v[214:217], v150 offset:53248
	ds_read_b128 v[218:221], v150 offset:54272
	ds_read_b128 v[222:225], v150 offset:55296
	ds_read_b128 v[226:229], v150 offset:56320
	s_setprio 1
	global_load_lds_dwordx4 v[146:147], off
	s_add_i32 m0, s54, 0x2000
	s_add_u32 s42, s42, 0x18080
	v_lshl_add_u64 v[146:147], v[204:205], 0, s[28:29]
	s_addc_u32 s43, s43, 0
	s_add_i32 s54, s71, s10
	global_load_lds_dwordx4 v[146:147], off
	v_lshl_add_u64 v[146:147], s[42:43], 0, v[98:99]
	s_mov_b32 m0, s54
	s_nop 0
	global_load_lds_dwordx4 v[146:147], off
	v_lshl_add_u64 v[146:147], s[42:43], 0, v[136:137]
	s_add_i32 m0, s54, 0x2000
	s_nop 0
	global_load_lds_dwordx4 v[146:147], off
	v_lshl_add_u64 v[146:147], v[206:207], 0, s[28:29]
	s_mov_b32 m0, s17
	s_nop 0
	global_load_lds_dwordx4 v[146:147], off
	v_lshl_add_u64 v[146:147], v[208:209], 0, s[28:29]
	s_mov_b32 m0, s18
	s_nop 0
	global_load_lds_dwordx4 v[146:147], off
	s_waitcnt vmcnt(8) lgkmcnt(0)
	s_barrier
	v_mfma_f32_16x16x32_bf16 v[62:65], v[152:155], v[184:187], v[62:65]
	v_mfma_f32_16x16x32_bf16 v[58:61], v[160:163], v[184:187], v[58:61]
	v_mfma_f32_16x16x32_bf16 v[46:49], v[152:155], v[192:195], v[46:49]
	v_mfma_f32_16x16x32_bf16 v[42:45], v[160:163], v[192:195], v[42:45]
	v_mfma_f32_16x16x32_bf16 v[30:33], v[152:155], v[214:217], v[30:33]
	v_mfma_f32_16x16x32_bf16 v[26:29], v[160:163], v[214:217], v[26:29]
	v_mfma_f32_16x16x32_bf16 v[14:17], v[152:155], v[222:225], v[14:17]
	v_mfma_f32_16x16x32_bf16 v[10:13], v[160:163], v[222:225], v[10:13]
	v_mfma_f32_16x16x32_bf16 v[62:65], v[156:159], v[188:191], v[62:65]
	v_mfma_f32_16x16x32_bf16 v[58:61], v[164:167], v[188:191], v[58:61]
	v_mfma_f32_16x16x32_bf16 v[46:49], v[156:159], v[196:199], v[46:49]
	v_mfma_f32_16x16x32_bf16 v[42:45], v[164:167], v[196:199], v[42:45]
	v_mfma_f32_16x16x32_bf16 v[30:33], v[156:159], v[218:221], v[30:33]
	v_mfma_f32_16x16x32_bf16 v[26:29], v[164:167], v[218:221], v[26:29]
	v_mfma_f32_16x16x32_bf16 v[14:17], v[156:159], v[226:229], v[14:17]
	v_mfma_f32_16x16x32_bf16 v[10:13], v[164:167], v[226:229], v[10:13]
	s_setprio 0
	s_setprio 1
	v_mfma_f32_16x16x32_bf16 v[54:57], v[168:171], v[184:187], v[54:57]
	v_mfma_f32_16x16x32_bf16 v[50:53], v[176:179], v[184:187], v[50:53]
	v_mfma_f32_16x16x32_bf16 v[38:41], v[168:171], v[192:195], v[38:41]
	v_mfma_f32_16x16x32_bf16 v[34:37], v[176:179], v[192:195], v[34:37]
	v_mfma_f32_16x16x32_bf16 v[22:25], v[168:171], v[214:217], v[22:25]
	v_mfma_f32_16x16x32_bf16 v[18:21], v[176:179], v[214:217], v[18:21]
	v_mfma_f32_16x16x32_bf16 v[6:9], v[168:171], v[222:225], v[6:9]
	v_mfma_f32_16x16x32_bf16 v[2:5], v[176:179], v[222:225], v[2:5]
	v_mfma_f32_16x16x32_bf16 v[54:57], v[172:175], v[188:191], v[54:57]
	v_mfma_f32_16x16x32_bf16 v[50:53], v[180:183], v[188:191], v[50:53]
	v_mfma_f32_16x16x32_bf16 v[38:41], v[172:175], v[196:199], v[38:41]
	v_mfma_f32_16x16x32_bf16 v[34:37], v[180:183], v[196:199], v[34:37]
	v_mfma_f32_16x16x32_bf16 v[22:25], v[172:175], v[218:221], v[22:25]
	v_mfma_f32_16x16x32_bf16 v[18:21], v[180:183], v[218:221], v[18:21]
	v_mfma_f32_16x16x32_bf16 v[6:9], v[172:175], v[226:229], v[6:9]
	v_mfma_f32_16x16x32_bf16 v[2:5], v[180:183], v[226:229], v[2:5]
	s_setprio 0
	s_barrier
	s_add_u32 s40, s40, 0x100
	s_addc_u32 s41, s41, 0
	s_add_u32 s66, s66, 0x100
	s_addc_u32 s67, s67, 0
	s_cmp_ge_i32 s68, s62
	s_mov_b32 s42, s68
	s_cbranch_scc0 .LBB0_647
	s_and_b64 vcc, exec, s[44:45]
	s_cbranch_vccz .LBB0_650
	s_barrier

.LBB0_893:
	s_add_u32 s50, s48, 0xfffe0080
	s_addc_u32 s51, s49, -1
	s_add_i32 s57, 0, 0x10000
	s_cmp_eq_u32 s56, 4
	s_cselect_b32 s53, s19, s51
	s_cselect_b32 s52, s33, s50
	v_add_u32_e32 v98, s57, v144
	s_cselect_b32 s51, s37, s55
	s_cselect_b32 s50, s39, s54
	s_add_i32 s60, 0, 0x14000
	ds_read_b128 v[146:149], v98
	ds_read_b128 v[150:153], v98 offset:1024
	ds_read_b128 v[154:157], v98 offset:2048
	ds_read_b128 v[158:161], v98 offset:3072
	v_add_u32_e32 v98, s60, v144
	ds_read_b128 v[162:165], v98
	ds_read_b128 v[166:169], v98 offset:1024
	ds_read_b128 v[170:173], v98 offset:2048
	ds_read_b128 v[174:177], v98 offset:3072
	v_lshl_add_u64 v[198:199], s[48:49], 0, v[140:141]
	s_add_i32 m0, s4, 0xc000
	ds_read_b128 v[178:181], v145
	ds_read_b128 v[182:185], v145 offset:1024
	ds_read_b128 v[186:189], v145 offset:2048
	ds_read_b128 v[190:193], v145 offset:3072
	ds_read_b128 v[194:197], v145 offset:4096
	ds_read_b128 v[204:207], v145 offset:5120
	ds_read_b128 v[208:211], v145 offset:6144
	ds_read_b128 v[214:217], v145 offset:7168
	s_setprio 1
	global_load_lds_dwordx4 v[198:199], off
	v_lshl_add_u64 v[198:199], s[48:49], 0, v[142:143]
	s_add_i32 m0, s4, 0xe000
	s_nop 0
	global_load_lds_dwordx4 v[198:199], off
	s_waitcnt vmcnt(8) lgkmcnt(0)
	s_barrier
	v_mfma_f32_16x16x32_bf16 v[128:131], v[146:149], v[178:181], v[128:131]
	v_mfma_f32_16x16x32_bf16 v[124:127], v[154:157], v[178:181], v[124:127]
	v_mfma_f32_16x16x32_bf16 v[112:115], v[146:149], v[186:189], v[112:115]
	v_mfma_f32_16x16x32_bf16 v[108:111], v[154:157], v[186:189], v[108:111]
	v_mfma_f32_16x16x32_bf16 v[94:97], v[146:149], v[194:197], v[94:97]
	v_mfma_f32_16x16x32_bf16 v[90:93], v[154:157], v[194:197], v[90:93]
	v_mfma_f32_16x16x32_bf16 v[78:81], v[146:149], v[208:211], v[78:81]
	v_mfma_f32_16x16x32_bf16 v[74:77], v[154:157], v[208:211], v[74:77]
	v_mfma_f32_16x16x32_bf16 v[128:131], v[150:153], v[182:185], v[128:131]
	v_mfma_f32_16x16x32_bf16 v[124:127], v[158:161], v[182:185], v[124:127]
	v_mfma_f32_16x16x32_bf16 v[112:115], v[150:153], v[190:193], v[112:115]
	v_mfma_f32_16x16x32_bf16 v[108:111], v[158:161], v[190:193], v[108:111]
	v_mfma_f32_16x16x32_bf16 v[94:97], v[150:153], v[204:207], v[94:97]
	v_mfma_f32_16x16x32_bf16 v[90:93], v[158:161], v[204:207], v[90:93]
	v_mfma_f32_16x16x32_bf16 v[78:81], v[150:153], v[214:217], v[78:81]
	v_mfma_f32_16x16x32_bf16 v[74:77], v[158:161], v[214:217], v[74:77]
	s_setprio 0
	s_setprio 1
	v_mfma_f32_16x16x32_bf16 v[120:123], v[162:165], v[178:181], v[120:123]
	v_mfma_f32_16x16x32_bf16 v[116:119], v[170:173], v[178:181], v[116:119]
	v_mfma_f32_16x16x32_bf16 v[104:107], v[162:165], v[186:189], v[104:107]
	v_mfma_f32_16x16x32_bf16 v[100:103], v[170:173], v[186:189], v[100:103]
	v_mfma_f32_16x16x32_bf16 v[86:89], v[162:165], v[194:197], v[86:89]
	v_mfma_f32_16x16x32_bf16 v[82:85], v[170:173], v[194:197], v[82:85]
	v_mfma_f32_16x16x32_bf16 v[70:73], v[162:165], v[208:211], v[70:73]
	v_mfma_f32_16x16x32_bf16 v[66:69], v[170:173], v[208:211], v[66:69]
	v_mfma_f32_16x16x32_bf16 v[120:123], v[166:169], v[182:185], v[120:123]
	v_mfma_f32_16x16x32_bf16 v[116:119], v[174:177], v[182:185], v[116:119]
	v_mfma_f32_16x16x32_bf16 v[104:107], v[166:169], v[190:193], v[104:107]
	v_mfma_f32_16x16x32_bf16 v[100:103], v[174:177], v[190:193], v[100:103]
	v_mfma_f32_16x16x32_bf16 v[86:89], v[166:169], v[204:207], v[86:89]
	v_mfma_f32_16x16x32_bf16 v[82:85], v[174:177], v[204:207], v[82:85]
	v_mfma_f32_16x16x32_bf16 v[70:73], v[166:169], v[214:217], v[70:73]
	v_mfma_f32_16x16x32_bf16 v[66:69], v[174:177], v[214:217], v[66:69]
	s_setprio 0
	s_barrier
	s_add_i32 s57, s57, s2
	v_lshl_add_u64 v[198:199], s[50:51], 0, v[136:137]
	s_mov_b32 m0, s57
	ds_read_b128 v[178:181], v145 offset:16384
	ds_read_b128 v[182:185], v145 offset:17408
	ds_read_b128 v[186:189], v145 offset:18432
	ds_read_b128 v[190:193], v145 offset:19456
	ds_read_b128 v[194:197], v145 offset:20480
	ds_read_b128 v[204:207], v145 offset:21504
	ds_read_b128 v[208:211], v145 offset:22528
	ds_read_b128 v[214:217], v145 offset:23552
	s_setprio 1
	global_load_lds_dwordx4 v[198:199], off
	s_add_i32 m0, s57, 0x2000
	s_add_u32 s58, s50, 0x20000
	v_lshl_add_u64 v[218:219], s[50:51], 0, v[132:133]
	s_addc_u32 s59, s51, 0
	s_add_i32 s57, s60, s2
	global_load_lds_dwordx4 v[218:219], off
	v_lshl_add_u64 v[220:221], s[58:59], 0, v[136:137]
	s_mov_b32 m0, s57
	v_lshl_add_u64 v[222:223], s[52:53], 0, v[134:135]
	global_load_lds_dwordx4 v[220:221], off
	v_lshl_add_u64 v[220:221], s[58:59], 0, v[132:133]
	s_add_i32 m0, s57, 0x2000
	s_nop 0
	global_load_lds_dwordx4 v[220:221], off
	v_lshl_add_u64 v[220:221], s[52:53], 0, v[138:139]
	s_mov_b32 m0, s4
	s_nop 0
	global_load_lds_dwordx4 v[220:221], off
	s_mov_b32 m0, s7
	s_nop 0
	global_load_lds_dwordx4 v[222:223], off
	s_waitcnt vmcnt(8) lgkmcnt(0)
	s_barrier
	v_mfma_f32_16x16x32_bf16 v[62:65], v[146:149], v[178:181], v[62:65]
	v_mfma_f32_16x16x32_bf16 v[58:61], v[154:157], v[178:181], v[58:61]
	v_mfma_f32_16x16x32_bf16 v[46:49], v[146:149], v[186:189], v[46:49]
	v_mfma_f32_16x16x32_bf16 v[42:45], v[154:157], v[186:189], v[42:45]
	v_mfma_f32_16x16x32_bf16 v[30:33], v[146:149], v[194:197], v[30:33]
	v_mfma_f32_16x16x32_bf16 v[26:29], v[154:157], v[194:197], v[26:29]
	v_mfma_f32_16x16x32_bf16 v[14:17], v[146:149], v[208:211], v[14:17]
	v_mfma_f32_16x16x32_bf16 v[10:13], v[154:157], v[208:211], v[10:13]
	v_mfma_f32_16x16x32_bf16 v[62:65], v[150:153], v[182:185], v[62:65]
	v_mfma_f32_16x16x32_bf16 v[58:61], v[158:161], v[182:185], v[58:61]
	v_mfma_f32_16x16x32_bf16 v[46:49], v[150:153], v[190:193], v[46:49]
	v_mfma_f32_16x16x32_bf16 v[42:45], v[158:161], v[190:193], v[42:45]
	v_mfma_f32_16x16x32_bf16 v[30:33], v[150:153], v[204:207], v[30:33]
	v_mfma_f32_16x16x32_bf16 v[26:29], v[158:161], v[204:207], v[26:29]
	v_mfma_f32_16x16x32_bf16 v[14:17], v[150:153], v[214:217], v[14:17]
	v_mfma_f32_16x16x32_bf16 v[10:13], v[158:161], v[214:217], v[10:13]
	s_setprio 0
	s_setprio 1
	v_mfma_f32_16x16x32_bf16 v[54:57], v[162:165], v[178:181], v[54:57]
	v_mfma_f32_16x16x32_bf16 v[50:53], v[170:173], v[178:181], v[50:53]
	v_mfma_f32_16x16x32_bf16 v[38:41], v[162:165], v[186:189], v[38:41]
	v_mfma_f32_16x16x32_bf16 v[34:37], v[170:173], v[186:189], v[34:37]
	v_mfma_f32_16x16x32_bf16 v[22:25], v[162:165], v[194:197], v[22:25]
	v_mfma_f32_16x16x32_bf16 v[18:21], v[170:173], v[194:197], v[18:21]
	v_mfma_f32_16x16x32_bf16 v[6:9], v[162:165], v[208:211], v[6:9]
	v_mfma_f32_16x16x32_bf16 v[2:5], v[170:173], v[208:211], v[2:5]
	v_mfma_f32_16x16x32_bf16 v[54:57], v[166:169], v[182:185], v[54:57]
	v_mfma_f32_16x16x32_bf16 v[50:53], v[174:177], v[182:185], v[50:53]
	v_mfma_f32_16x16x32_bf16 v[38:41], v[166:169], v[190:193], v[38:41]
	v_mfma_f32_16x16x32_bf16 v[34:37], v[174:177], v[190:193], v[34:37]
	v_mfma_f32_16x16x32_bf16 v[22:25], v[166:169], v[204:207], v[22:25]
	v_mfma_f32_16x16x32_bf16 v[18:21], v[174:177], v[204:207], v[18:21]
	v_mfma_f32_16x16x32_bf16 v[6:9], v[166:169], v[214:217], v[6:9]
	v_mfma_f32_16x16x32_bf16 v[2:5], v[174:177], v[214:217], v[2:5]
	s_setprio 0
	s_barrier
	s_add_i32 s57, 0, 0x18000
	v_add_u32_e32 v98, s57, v144
	s_add_i32 s58, 0, 0x1c000
	ds_read_b128 v[146:149], v98
	ds_read_b128 v[150:153], v98 offset:1024
	ds_read_b128 v[154:157], v98 offset:2048
	ds_read_b128 v[158:161], v98 offset:3072
	v_add_u32_e32 v98, s58, v144
	ds_read_b128 v[162:165], v98
	ds_read_b128 v[166:169], v98 offset:1024
	ds_read_b128 v[170:173], v98 offset:2048
	ds_read_b128 v[174:177], v98 offset:3072
	s_add_u32 s52, s52, 0x20000
	s_addc_u32 s53, s53, 0
	s_mov_b32 m0, s8
	v_lshl_add_u64 v[224:225], s[52:53], 0, v[138:139]
	ds_read_b128 v[178:181], v145 offset:32768
	ds_read_b128 v[182:185], v145 offset:33792
	ds_read_b128 v[186:189], v145 offset:34816
	ds_read_b128 v[190:193], v145 offset:35840
	ds_read_b128 v[194:197], v145 offset:36864
	ds_read_b128 v[204:207], v145 offset:37888
	ds_read_b128 v[208:211], v145 offset:38912
	ds_read_b128 v[214:217], v145 offset:39936
	s_setprio 1
	global_load_lds_dwordx4 v[224:225], off
	v_lshl_add_u64 v[224:225], s[52:53], 0, v[134:135]
	s_mov_b32 m0, s9
	s_nop 0
	global_load_lds_dwordx4 v[224:225], off
	s_waitcnt vmcnt(8) lgkmcnt(0)
	s_barrier
	v_mfma_f32_16x16x32_bf16 v[128:131], v[146:149], v[178:181], v[128:131]
	v_mfma_f32_16x16x32_bf16 v[124:127], v[154:157], v[178:181], v[124:127]
	v_mfma_f32_16x16x32_bf16 v[112:115], v[146:149], v[186:189], v[112:115]
	v_mfma_f32_16x16x32_bf16 v[108:111], v[154:157], v[186:189], v[108:111]
	v_mfma_f32_16x16x32_bf16 v[94:97], v[146:149], v[194:197], v[94:97]
	v_mfma_f32_16x16x32_bf16 v[90:93], v[154:157], v[194:197], v[90:93]
	v_mfma_f32_16x16x32_bf16 v[78:81], v[146:149], v[208:211], v[78:81]
	v_mfma_f32_16x16x32_bf16 v[74:77], v[154:157], v[208:211], v[74:77]
	v_mfma_f32_16x16x32_bf16 v[128:131], v[150:153], v[182:185], v[128:131]
	v_mfma_f32_16x16x32_bf16 v[124:127], v[158:161], v[182:185], v[124:127]
	v_mfma_f32_16x16x32_bf16 v[112:115], v[150:153], v[190:193], v[112:115]
	v_mfma_f32_16x16x32_bf16 v[108:111], v[158:161], v[190:193], v[108:111]
	v_mfma_f32_16x16x32_bf16 v[94:97], v[150:153], v[204:207], v[94:97]
	v_mfma_f32_16x16x32_bf16 v[90:93], v[158:161], v[204:207], v[90:93]
	v_mfma_f32_16x16x32_bf16 v[78:81], v[150:153], v[214:217], v[78:81]
	v_mfma_f32_16x16x32_bf16 v[74:77], v[158:161], v[214:217], v[74:77]
	s_setprio 0
	s_setprio 1
	v_mfma_f32_16x16x32_bf16 v[120:123], v[162:165], v[178:181], v[120:123]
	v_mfma_f32_16x16x32_bf16 v[116:119], v[170:173], v[178:181], v[116:119]
	v_mfma_f32_16x16x32_bf16 v[104:107], v[162:165], v[186:189], v[104:107]
	v_mfma_f32_16x16x32_bf16 v[100:103], v[170:173], v[186:189], v[100:103]
	v_mfma_f32_16x16x32_bf16 v[86:89], v[162:165], v[194:197], v[86:89]
	v_mfma_f32_16x16x32_bf16 v[82:85], v[170:173], v[194:197], v[82:85]
	v_mfma_f32_16x16x32_bf16 v[70:73], v[162:165], v[208:211], v[70:73]
	v_mfma_f32_16x16x32_bf16 v[66:69], v[170:173], v[208:211], v[66:69]
	v_mfma_f32_16x16x32_bf16 v[120:123], v[166:169], v[182:185], v[120:123]
	v_mfma_f32_16x16x32_bf16 v[116:119], v[174:177], v[182:185], v[116:119]
	v_mfma_f32_16x16x32_bf16 v[104:107], v[166:169], v[190:193], v[104:107]
	v_mfma_f32_16x16x32_bf16 v[100:103], v[174:177], v[190:193], v[100:103]
	v_mfma_f32_16x16x32_bf16 v[86:89], v[166:169], v[204:207], v[86:89]
	v_mfma_f32_16x16x32_bf16 v[82:85], v[174:177], v[204:207], v[82:85]
	v_mfma_f32_16x16x32_bf16 v[70:73], v[166:169], v[214:217], v[70:73]
	v_mfma_f32_16x16x32_bf16 v[66:69], v[174:177], v[214:217], v[66:69]
	s_setprio 0
	s_barrier
	s_add_i32 s52, s57, s2
	v_lshl_add_u64 v[198:199], v[198:199], 0, s[28:29]
	s_mov_b32 m0, s52
	ds_read_b128 v[178:181], v145 offset:49152
	ds_read_b128 v[182:185], v145 offset:50176
	ds_read_b128 v[186:189], v145 offset:51200
	ds_read_b128 v[190:193], v145 offset:52224
	ds_read_b128 v[194:197], v145 offset:53248
	ds_read_b128 v[204:207], v145 offset:54272
	ds_read_b128 v[208:211], v145 offset:55296
	ds_read_b128 v[214:217], v145 offset:56320
	s_setprio 1
	global_load_lds_dwordx4 v[198:199], off
	s_add_i32 m0, s52, 0x2000
	s_add_u32 s50, s50, 0x20080
	v_lshl_add_u64 v[198:199], v[218:219], 0, s[28:29]
	s_addc_u32 s51, s51, 0
	s_add_i32 s52, s58, s2
	global_load_lds_dwordx4 v[198:199], off
	v_lshl_add_u64 v[198:199], s[50:51], 0, v[136:137]
	s_mov_b32 m0, s52
	s_nop 0
	global_load_lds_dwordx4 v[198:199], off
	v_lshl_add_u64 v[198:199], s[50:51], 0, v[132:133]
	s_add_i32 m0, s52, 0x2000
	s_nop 0
	global_load_lds_dwordx4 v[198:199], off
	v_lshl_add_u64 v[198:199], v[220:221], 0, s[28:29]
	s_mov_b32 m0, s12
	s_nop 0
	global_load_lds_dwordx4 v[198:199], off
	v_lshl_add_u64 v[198:199], v[222:223], 0, s[28:29]
	s_mov_b32 m0, s13
	s_nop 0
	global_load_lds_dwordx4 v[198:199], off
	s_waitcnt vmcnt(8) lgkmcnt(0)
	s_barrier
	v_mfma_f32_16x16x32_bf16 v[62:65], v[146:149], v[178:181], v[62:65]
	v_mfma_f32_16x16x32_bf16 v[58:61], v[154:157], v[178:181], v[58:61]
	v_mfma_f32_16x16x32_bf16 v[46:49], v[146:149], v[186:189], v[46:49]
	v_mfma_f32_16x16x32_bf16 v[42:45], v[154:157], v[186:189], v[42:45]
	v_mfma_f32_16x16x32_bf16 v[30:33], v[146:149], v[194:197], v[30:33]
	v_mfma_f32_16x16x32_bf16 v[26:29], v[154:157], v[194:197], v[26:29]
	v_mfma_f32_16x16x32_bf16 v[14:17], v[146:149], v[208:211], v[14:17]
	v_mfma_f32_16x16x32_bf16 v[10:13], v[154:157], v[208:211], v[10:13]
	v_mfma_f32_16x16x32_bf16 v[62:65], v[150:153], v[182:185], v[62:65]
	v_mfma_f32_16x16x32_bf16 v[58:61], v[158:161], v[182:185], v[58:61]
	v_mfma_f32_16x16x32_bf16 v[46:49], v[150:153], v[190:193], v[46:49]
	v_mfma_f32_16x16x32_bf16 v[42:45], v[158:161], v[190:193], v[42:45]
	v_mfma_f32_16x16x32_bf16 v[30:33], v[150:153], v[204:207], v[30:33]
	v_mfma_f32_16x16x32_bf16 v[26:29], v[158:161], v[204:207], v[26:29]
	v_mfma_f32_16x16x32_bf16 v[14:17], v[150:153], v[214:217], v[14:17]
	v_mfma_f32_16x16x32_bf16 v[10:13], v[158:161], v[214:217], v[10:13]
	s_setprio 0
	s_setprio 1
	v_mfma_f32_16x16x32_bf16 v[54:57], v[162:165], v[178:181], v[54:57]
	v_mfma_f32_16x16x32_bf16 v[50:53], v[170:173], v[178:181], v[50:53]
	v_mfma_f32_16x16x32_bf16 v[38:41], v[162:165], v[186:189], v[38:41]
	v_mfma_f32_16x16x32_bf16 v[34:37], v[170:173], v[186:189], v[34:37]
	v_mfma_f32_16x16x32_bf16 v[22:25], v[162:165], v[194:197], v[22:25]
	v_mfma_f32_16x16x32_bf16 v[18:21], v[170:173], v[194:197], v[18:21]
	v_mfma_f32_16x16x32_bf16 v[6:9], v[162:165], v[208:211], v[6:9]
	v_mfma_f32_16x16x32_bf16 v[2:5], v[170:173], v[208:211], v[2:5]
	v_mfma_f32_16x16x32_bf16 v[54:57], v[166:169], v[182:185], v[54:57]
	v_mfma_f32_16x16x32_bf16 v[50:53], v[174:177], v[182:185], v[50:53]
	v_mfma_f32_16x16x32_bf16 v[38:41], v[166:169], v[190:193], v[38:41]
	v_mfma_f32_16x16x32_bf16 v[34:37], v[174:177], v[190:193], v[34:37]
	v_mfma_f32_16x16x32_bf16 v[22:25], v[166:169], v[204:207], v[22:25]
	v_mfma_f32_16x16x32_bf16 v[18:21], v[174:177], v[204:207], v[18:21]
	v_mfma_f32_16x16x32_bf16 v[6:9], v[166:169], v[214:217], v[6:9]
	v_mfma_f32_16x16x32_bf16 v[2:5], v[174:177], v[214:217], v[2:5]
	s_setprio 0
	s_barrier
	s_add_i32 s56, s56, 2
	s_add_u32 s48, s48, 0x100
	s_addc_u32 s49, s49, 0
	s_add_u32 s54, s54, 0x100
	s_addc_u32 s55, s55, 0
	s_cmp_gt_u32 s56, 5
	s_cbranch_scc0 .LBB0_893
	s_and_b64 vcc, exec, s[22:23]
	s_cbranch_vccz .LBB0_896
	s_barrier

.LBB0_1072:
	s_add_u32 s60, s56, s58
	s_addc_u32 s61, s57, s59
	s_add_u32 s60, s60, 0x100
	s_addc_u32 s61, s61, 0
	s_add_u32 s71, s66, s58
	s_addc_u32 s72, s67, s59
	s_add_i32 s73, 0, 0x10000
	s_cmpk_eq_i32 s58, 0x700
	s_cselect_b32 s63, s45, s61
	s_cselect_b32 s62, s51, s60
	v_add_u32_e32 v98, s73, v214
	s_cselect_b32 s61, s49, s72
	s_cselect_b32 s60, s65, s71
	s_add_i32 s71, 0, 0x14000
	ds_read_b128 v[138:141], v98
	ds_read_b128 v[142:145], v98 offset:1024
	ds_read_b128 v[146:149], v98 offset:2048
	ds_read_b128 v[150:153], v98 offset:3072
	v_add_u32_e32 v98, s71, v214
	ds_read_b128 v[154:157], v98
	ds_read_b128 v[158:161], v98 offset:1024
	ds_read_b128 v[162:165], v98 offset:2048
	ds_read_b128 v[166:169], v98 offset:3072
	v_lshl_add_u64 v[100:101], v[134:135], 0, s[58:59]
	s_add_i32 m0, s9, 0xc000
	ds_read_b128 v[170:173], v218
	ds_read_b128 v[186:189], v218 offset:1024
	ds_read_b128 v[190:193], v218 offset:2048
	ds_read_b128 v[194:197], v218 offset:3072
	ds_read_b128 v[204:207], v218 offset:4096
	ds_read_b128 v[208:211], v218 offset:5120
	ds_read_b128 v[220:223], v218 offset:6144
	ds_read_b128 v[224:227], v218 offset:7168
	s_setprio 1
	global_load_lds_dwordx4 v[100:101], off
	v_lshl_add_u64 v[100:101], v[136:137], 0, s[58:59]
	s_add_i32 m0, s9, 0xe000
	s_nop 0
	global_load_lds_dwordx4 v[100:101], off
	s_waitcnt vmcnt(8) lgkmcnt(0)
	s_barrier
	v_mfma_f32_16x16x32_bf16 v[130:133], v[138:141], v[170:173], v[130:133]
	v_mfma_f32_16x16x32_bf16 v[126:129], v[146:149], v[170:173], v[126:129]
	v_mfma_f32_16x16x32_bf16 v[122:125], v[138:141], v[190:193], v[122:125]
	v_mfma_f32_16x16x32_bf16 v[118:121], v[146:149], v[190:193], v[118:121]
	v_mfma_f32_16x16x32_bf16 v[114:117], v[138:141], v[204:207], v[114:117]
	v_mfma_f32_16x16x32_bf16 v[110:113], v[146:149], v[204:207], v[110:113]
	v_mfma_f32_16x16x32_bf16 v[106:109], v[138:141], v[220:223], v[106:109]
	v_mfma_f32_16x16x32_bf16 v[100:103], v[146:149], v[220:223], v[102:105]
	v_mfma_f32_16x16x32_bf16 v[130:133], v[142:145], v[186:189], v[130:133]
	v_mfma_f32_16x16x32_bf16 v[126:129], v[150:153], v[186:189], v[126:129]
	v_mfma_f32_16x16x32_bf16 v[122:125], v[142:145], v[194:197], v[122:125]
	v_mfma_f32_16x16x32_bf16 v[118:121], v[150:153], v[194:197], v[118:121]
	v_mfma_f32_16x16x32_bf16 v[114:117], v[142:145], v[208:211], v[114:117]
	v_mfma_f32_16x16x32_bf16 v[110:113], v[150:153], v[208:211], v[110:113]
	v_mfma_f32_16x16x32_bf16 v[106:109], v[142:145], v[224:227], v[106:109]
	v_mfma_f32_16x16x32_bf16 v[100:103], v[150:153], v[224:227], v[100:103]
	s_setprio 0
	s_setprio 1
	v_mfma_f32_16x16x32_bf16 v[62:65], v[154:157], v[170:173], v[62:65]
	v_mfma_f32_16x16x32_bf16 v[58:61], v[162:165], v[170:173], v[58:61]
	v_mfma_f32_16x16x32_bf16 v[54:57], v[154:157], v[190:193], v[54:57]
	v_mfma_f32_16x16x32_bf16 v[50:53], v[162:165], v[190:193], v[50:53]
	v_mfma_f32_16x16x32_bf16 v[46:49], v[154:157], v[204:207], v[46:49]
	v_mfma_f32_16x16x32_bf16 v[42:45], v[162:165], v[204:207], v[42:45]
	v_mfma_f32_16x16x32_bf16 v[38:41], v[154:157], v[220:223], v[38:41]
	v_mfma_f32_16x16x32_bf16 v[34:37], v[162:165], v[220:223], v[34:37]
	v_mfma_f32_16x16x32_bf16 v[62:65], v[158:161], v[186:189], v[62:65]
	v_mfma_f32_16x16x32_bf16 v[58:61], v[166:169], v[186:189], v[58:61]
	v_mfma_f32_16x16x32_bf16 v[54:57], v[158:161], v[194:197], v[54:57]
	v_mfma_f32_16x16x32_bf16 v[50:53], v[166:169], v[194:197], v[50:53]
	v_mfma_f32_16x16x32_bf16 v[46:49], v[158:161], v[208:211], v[46:49]
	v_mfma_f32_16x16x32_bf16 v[42:45], v[166:169], v[208:211], v[42:45]
	v_mfma_f32_16x16x32_bf16 v[38:41], v[158:161], v[224:227], v[38:41]
	v_mfma_f32_16x16x32_bf16 v[34:37], v[166:169], v[224:227], v[34:37]
	s_setprio 0
	s_barrier
	s_add_i32 s72, s73, s4
	v_lshl_add_u64 v[198:199], s[60:61], 0, v[176:177]
	s_mov_b32 m0, s72
	ds_read_b128 v[170:173], v218 offset:16384
	ds_read_b128 v[186:189], v218 offset:17408
	ds_read_b128 v[190:193], v218 offset:18432
	ds_read_b128 v[194:197], v218 offset:19456
	ds_read_b128 v[204:207], v218 offset:20480
	ds_read_b128 v[208:211], v218 offset:21504
	ds_read_b128 v[220:223], v218 offset:22528
	ds_read_b128 v[224:227], v218 offset:23552
	s_setprio 1
	global_load_lds_dwordx4 v[198:199], off
	s_add_i32 m0, s72, 0x2000
	s_add_u32 s72, s60, 0x40000
	v_lshl_add_u64 v[228:229], s[60:61], 0, v[180:181]
	s_addc_u32 s73, s61, 0
	s_add_i32 s71, s71, s4
	global_load_lds_dwordx4 v[228:229], off
	v_lshl_add_u64 v[104:105], s[72:73], 0, v[176:177]
	s_mov_b32 m0, s71
	v_lshl_add_u64 v[230:231], s[62:63], 0, v[174:175]
	global_load_lds_dwordx4 v[104:105], off
	v_lshl_add_u64 v[104:105], s[72:73], 0, v[180:181]
	s_add_i32 m0, s71, 0x2000
	v_lshl_add_u64 v[232:233], s[62:63], 0, v[178:179]
	global_load_lds_dwordx4 v[104:105], off
	s_mov_b32 m0, s9
	s_nop 0
	global_load_lds_dwordx4 v[230:231], off
	s_mov_b32 m0, s10
	s_nop 0
	global_load_lds_dwordx4 v[232:233], off
	s_waitcnt vmcnt(8) lgkmcnt(0)
	s_barrier
	v_mfma_f32_16x16x32_bf16 v[94:97], v[138:141], v[170:173], v[94:97]
	v_mfma_f32_16x16x32_bf16 v[90:93], v[146:149], v[170:173], v[90:93]
	v_mfma_f32_16x16x32_bf16 v[86:89], v[138:141], v[190:193], v[86:89]
	v_mfma_f32_16x16x32_bf16 v[82:85], v[146:149], v[190:193], v[82:85]
	v_mfma_f32_16x16x32_bf16 v[78:81], v[138:141], v[204:207], v[78:81]
	v_mfma_f32_16x16x32_bf16 v[74:77], v[146:149], v[204:207], v[74:77]
	v_mfma_f32_16x16x32_bf16 v[70:73], v[138:141], v[220:223], v[70:73]
	v_mfma_f32_16x16x32_bf16 v[66:69], v[146:149], v[220:223], v[66:69]
	v_mfma_f32_16x16x32_bf16 v[94:97], v[142:145], v[186:189], v[94:97]
	v_mfma_f32_16x16x32_bf16 v[90:93], v[150:153], v[186:189], v[90:93]
	v_mfma_f32_16x16x32_bf16 v[86:89], v[142:145], v[194:197], v[86:89]
	v_mfma_f32_16x16x32_bf16 v[82:85], v[150:153], v[194:197], v[82:85]
	v_mfma_f32_16x16x32_bf16 v[78:81], v[142:145], v[208:211], v[78:81]
	v_mfma_f32_16x16x32_bf16 v[74:77], v[150:153], v[208:211], v[74:77]
	v_mfma_f32_16x16x32_bf16 v[70:73], v[142:145], v[224:227], v[70:73]
	v_mfma_f32_16x16x32_bf16 v[66:69], v[150:153], v[224:227], v[66:69]
	s_setprio 0
	s_setprio 1
	v_mfma_f32_16x16x32_bf16 v[30:33], v[154:157], v[170:173], v[30:33]
	v_mfma_f32_16x16x32_bf16 v[26:29], v[162:165], v[170:173], v[26:29]
	v_mfma_f32_16x16x32_bf16 v[22:25], v[154:157], v[190:193], v[22:25]
	v_mfma_f32_16x16x32_bf16 v[18:21], v[162:165], v[190:193], v[18:21]
	v_mfma_f32_16x16x32_bf16 v[14:17], v[154:157], v[204:207], v[14:17]
	v_mfma_f32_16x16x32_bf16 v[10:13], v[162:165], v[204:207], v[10:13]
	v_mfma_f32_16x16x32_bf16 v[6:9], v[154:157], v[220:223], v[6:9]
	v_mfma_f32_16x16x32_bf16 v[2:5], v[162:165], v[220:223], v[2:5]
	v_mfma_f32_16x16x32_bf16 v[30:33], v[158:161], v[186:189], v[30:33]
	v_mfma_f32_16x16x32_bf16 v[26:29], v[166:169], v[186:189], v[26:29]
	v_mfma_f32_16x16x32_bf16 v[22:25], v[158:161], v[194:197], v[22:25]
	v_mfma_f32_16x16x32_bf16 v[18:21], v[166:169], v[194:197], v[18:21]
	v_mfma_f32_16x16x32_bf16 v[14:17], v[158:161], v[208:211], v[14:17]
	v_mfma_f32_16x16x32_bf16 v[10:13], v[166:169], v[208:211], v[10:13]
	v_mfma_f32_16x16x32_bf16 v[6:9], v[158:161], v[224:227], v[6:9]
	v_mfma_f32_16x16x32_bf16 v[2:5], v[166:169], v[224:227], v[2:5]
	s_setprio 0
	s_barrier
	s_add_i32 s71, 0, 0x18000
	v_add_u32_e32 v98, s71, v214
	s_add_i32 s72, 0, 0x1c000
	ds_read_b128 v[138:141], v98
	ds_read_b128 v[142:145], v98 offset:1024
	ds_read_b128 v[146:149], v98 offset:2048
	ds_read_b128 v[150:153], v98 offset:3072
	v_add_u32_e32 v98, s72, v214
	ds_read_b128 v[154:157], v98
	ds_read_b128 v[158:161], v98 offset:1024
	ds_read_b128 v[162:165], v98 offset:2048
	ds_read_b128 v[166:169], v98 offset:3072
	s_add_u32 s62, s62, 0x40000
	s_addc_u32 s63, s63, 0
	s_mov_b32 m0, s11
	v_lshl_add_u64 v[104:105], s[62:63], 0, v[174:175]
	ds_read_b128 v[170:173], v218 offset:32768
	ds_read_b128 v[186:189], v218 offset:33792
	ds_read_b128 v[190:193], v218 offset:34816
	ds_read_b128 v[194:197], v218 offset:35840
	ds_read_b128 v[204:207], v218 offset:36864
	ds_read_b128 v[208:211], v218 offset:37888
	ds_read_b128 v[220:223], v218 offset:38912
	ds_read_b128 v[224:227], v218 offset:39936
	s_setprio 1
	global_load_lds_dwordx4 v[104:105], off
	v_lshl_add_u64 v[104:105], s[62:63], 0, v[178:179]
	s_mov_b32 m0, s12
	s_nop 0
	global_load_lds_dwordx4 v[104:105], off
	s_waitcnt vmcnt(8) lgkmcnt(0)
	s_barrier
	v_mfma_f32_16x16x32_bf16 v[130:133], v[138:141], v[170:173], v[130:133]
	v_mfma_f32_16x16x32_bf16 v[126:129], v[146:149], v[170:173], v[126:129]
	v_mfma_f32_16x16x32_bf16 v[122:125], v[138:141], v[190:193], v[122:125]
	v_mfma_f32_16x16x32_bf16 v[118:121], v[146:149], v[190:193], v[118:121]
	v_mfma_f32_16x16x32_bf16 v[114:117], v[138:141], v[204:207], v[114:117]
	v_mfma_f32_16x16x32_bf16 v[110:113], v[146:149], v[204:207], v[110:113]
	v_mfma_f32_16x16x32_bf16 v[104:107], v[138:141], v[220:223], v[106:109]
	v_mfma_f32_16x16x32_bf16 v[100:103], v[146:149], v[220:223], v[100:103]
	v_mfma_f32_16x16x32_bf16 v[130:133], v[142:145], v[186:189], v[130:133]
	v_mfma_f32_16x16x32_bf16 v[126:129], v[150:153], v[186:189], v[126:129]
	v_mfma_f32_16x16x32_bf16 v[122:125], v[142:145], v[194:197], v[122:125]
	v_mfma_f32_16x16x32_bf16 v[118:121], v[150:153], v[194:197], v[118:121]
	v_mfma_f32_16x16x32_bf16 v[114:117], v[142:145], v[208:211], v[114:117]
	v_mfma_f32_16x16x32_bf16 v[110:113], v[150:153], v[208:211], v[110:113]
	v_mfma_f32_16x16x32_bf16 v[106:109], v[142:145], v[224:227], v[104:107]
	v_mfma_f32_16x16x32_bf16 v[102:105], v[150:153], v[224:227], v[100:103]
	s_setprio 0
	s_setprio 1
	v_mfma_f32_16x16x32_bf16 v[62:65], v[154:157], v[170:173], v[62:65]
	v_mfma_f32_16x16x32_bf16 v[58:61], v[162:165], v[170:173], v[58:61]
	v_mfma_f32_16x16x32_bf16 v[54:57], v[154:157], v[190:193], v[54:57]
	v_mfma_f32_16x16x32_bf16 v[50:53], v[162:165], v[190:193], v[50:53]
	v_mfma_f32_16x16x32_bf16 v[46:49], v[154:157], v[204:207], v[46:49]
	v_mfma_f32_16x16x32_bf16 v[42:45], v[162:165], v[204:207], v[42:45]
	v_mfma_f32_16x16x32_bf16 v[38:41], v[154:157], v[220:223], v[38:41]
	v_mfma_f32_16x16x32_bf16 v[34:37], v[162:165], v[220:223], v[34:37]
	v_mfma_f32_16x16x32_bf16 v[62:65], v[158:161], v[186:189], v[62:65]
	v_mfma_f32_16x16x32_bf16 v[58:61], v[166:169], v[186:189], v[58:61]
	v_mfma_f32_16x16x32_bf16 v[54:57], v[158:161], v[194:197], v[54:57]
	v_mfma_f32_16x16x32_bf16 v[50:53], v[166:169], v[194:197], v[50:53]
	v_mfma_f32_16x16x32_bf16 v[46:49], v[158:161], v[208:211], v[46:49]
	v_mfma_f32_16x16x32_bf16 v[42:45], v[166:169], v[208:211], v[42:45]
	v_mfma_f32_16x16x32_bf16 v[38:41], v[158:161], v[224:227], v[38:41]
	v_mfma_f32_16x16x32_bf16 v[34:37], v[166:169], v[224:227], v[34:37]
	s_setprio 0
	s_barrier
	s_add_i32 s62, s71, s4
	v_lshl_add_u64 v[100:101], v[198:199], 0, s[28:29]
	s_mov_b32 m0, s62
	ds_read_b128 v[170:173], v218 offset:49152
	ds_read_b128 v[186:189], v218 offset:50176
	ds_read_b128 v[190:193], v218 offset:51200
	ds_read_b128 v[194:197], v218 offset:52224
	ds_read_b128 v[204:207], v218 offset:53248
	ds_read_b128 v[208:211], v218 offset:54272
	ds_read_b128 v[220:223], v218 offset:55296
	ds_read_b128 v[224:227], v218 offset:56320
	s_setprio 1
	global_load_lds_dwordx4 v[100:101], off
	s_add_i32 m0, s62, 0x2000
	s_add_u32 s60, s60, 0x40080
	v_lshl_add_u64 v[100:101], v[228:229], 0, s[28:29]
	s_addc_u32 s61, s61, 0
	s_add_i32 s62, s72, s4
	global_load_lds_dwordx4 v[100:101], off
	v_lshl_add_u64 v[100:101], s[60:61], 0, v[176:177]
	s_mov_b32 m0, s62
	s_nop 0
	global_load_lds_dwordx4 v[100:101], off
	v_lshl_add_u64 v[100:101], s[60:61], 0, v[180:181]
	s_add_i32 m0, s62, 0x2000
	s_nop 0
	global_load_lds_dwordx4 v[100:101], off
	v_lshl_add_u64 v[100:101], v[230:231], 0, s[28:29]
	s_mov_b32 m0, s15
	s_nop 0
	global_load_lds_dwordx4 v[100:101], off
	v_lshl_add_u64 v[100:101], v[232:233], 0, s[28:29]
	s_mov_b32 m0, s16
	s_nop 0
	global_load_lds_dwordx4 v[100:101], off
	s_waitcnt vmcnt(8) lgkmcnt(0)
	s_barrier
	v_mfma_f32_16x16x32_bf16 v[94:97], v[138:141], v[170:173], v[94:97]
	v_mfma_f32_16x16x32_bf16 v[90:93], v[146:149], v[170:173], v[90:93]
	v_mfma_f32_16x16x32_bf16 v[86:89], v[138:141], v[190:193], v[86:89]
	v_mfma_f32_16x16x32_bf16 v[82:85], v[146:149], v[190:193], v[82:85]
	v_mfma_f32_16x16x32_bf16 v[78:81], v[138:141], v[204:207], v[78:81]
	v_mfma_f32_16x16x32_bf16 v[74:77], v[146:149], v[204:207], v[74:77]
	v_mfma_f32_16x16x32_bf16 v[70:73], v[138:141], v[220:223], v[70:73]
	v_mfma_f32_16x16x32_bf16 v[66:69], v[146:149], v[220:223], v[66:69]
	v_mfma_f32_16x16x32_bf16 v[94:97], v[142:145], v[186:189], v[94:97]
	v_mfma_f32_16x16x32_bf16 v[90:93], v[150:153], v[186:189], v[90:93]
	v_mfma_f32_16x16x32_bf16 v[86:89], v[142:145], v[194:197], v[86:89]
	v_mfma_f32_16x16x32_bf16 v[82:85], v[150:153], v[194:197], v[82:85]
	v_mfma_f32_16x16x32_bf16 v[78:81], v[142:145], v[208:211], v[78:81]
	v_mfma_f32_16x16x32_bf16 v[74:77], v[150:153], v[208:211], v[74:77]
	v_mfma_f32_16x16x32_bf16 v[70:73], v[142:145], v[224:227], v[70:73]
	v_mfma_f32_16x16x32_bf16 v[66:69], v[150:153], v[224:227], v[66:69]
	s_setprio 0
	s_setprio 1
	v_mfma_f32_16x16x32_bf16 v[30:33], v[154:157], v[170:173], v[30:33]
	v_mfma_f32_16x16x32_bf16 v[26:29], v[162:165], v[170:173], v[26:29]
	v_mfma_f32_16x16x32_bf16 v[22:25], v[154:157], v[190:193], v[22:25]
	v_mfma_f32_16x16x32_bf16 v[18:21], v[162:165], v[190:193], v[18:21]
	v_mfma_f32_16x16x32_bf16 v[14:17], v[154:157], v[204:207], v[14:17]
	v_mfma_f32_16x16x32_bf16 v[10:13], v[162:165], v[204:207], v[10:13]
	v_mfma_f32_16x16x32_bf16 v[6:9], v[154:157], v[220:223], v[6:9]
	v_mfma_f32_16x16x32_bf16 v[2:5], v[162:165], v[220:223], v[2:5]
	v_mfma_f32_16x16x32_bf16 v[30:33], v[158:161], v[186:189], v[30:33]
	v_mfma_f32_16x16x32_bf16 v[26:29], v[166:169], v[186:189], v[26:29]
	v_mfma_f32_16x16x32_bf16 v[22:25], v[158:161], v[194:197], v[22:25]
	v_mfma_f32_16x16x32_bf16 v[18:21], v[166:169], v[194:197], v[18:21]
	v_mfma_f32_16x16x32_bf16 v[14:17], v[158:161], v[208:211], v[14:17]
	v_mfma_f32_16x16x32_bf16 v[10:13], v[166:169], v[208:211], v[10:13]
	v_mfma_f32_16x16x32_bf16 v[6:9], v[158:161], v[224:227], v[6:9]
	v_mfma_f32_16x16x32_bf16 v[2:5], v[166:169], v[224:227], v[2:5]
	s_setprio 0
	s_barrier
	s_add_u32 s58, s58, 0x100
	s_addc_u32 s59, s59, 0
	s_cmp_gt_u32 s70, 13
	s_cbranch_scc1 .LBB0_1075

.LBB0_1110:
	s_add_i32 s75, s75, 2
	s_add_u32 s60, s38, s58
	s_addc_u32 s61, s39, s59
	s_add_u32 s60, s60, 0x100
	s_addc_u32 s61, s61, 0
	s_add_u32 s76, s72, s58
	s_addc_u32 s77, s73, s59
	s_add_i32 s78, 0, 0x10000
	s_cmp_eq_u32 s74, s58
	s_cselect_b32 s63, s49, s61
	s_cselect_b32 s62, s70, s60
	v_add_u32_e32 v98, s78, v177
	s_cselect_b32 s61, s45, s77
	s_cselect_b32 s60, s71, s76
	s_add_i32 s79, 0, 0x14000
	ds_read_b128 v[138:141], v98
	ds_read_b128 v[142:145], v98 offset:1024
	ds_read_b128 v[146:149], v98 offset:2048
	ds_read_b128 v[150:153], v98 offset:3072
	v_add_u32_e32 v98, s79, v177
	ds_read_b128 v[154:157], v98
	ds_read_b128 v[170:173], v98 offset:1024
	ds_read_b128 v[182:185], v98 offset:2048
	ds_read_b128 v[186:189], v98 offset:3072
	v_lshl_add_u64 v[100:101], v[134:135], 0, s[58:59]
	s_add_i32 m0, s10, 0xc000
	ds_read_b128 v[190:193], v181
	ds_read_b128 v[194:197], v181 offset:1024
	ds_read_b128 v[204:207], v181 offset:2048
	ds_read_b128 v[208:211], v181 offset:3072
	ds_read_b128 v[214:217], v181 offset:4096
	ds_read_b128 v[218:221], v181 offset:5120
	ds_read_b128 v[222:225], v181 offset:6144
	ds_read_b128 v[226:229], v181 offset:7168
	s_setprio 1
	global_load_lds_dwordx4 v[100:101], off
	v_lshl_add_u64 v[100:101], v[136:137], 0, s[58:59]
	s_add_i32 m0, s10, 0xe000
	s_nop 0
	global_load_lds_dwordx4 v[100:101], off
	s_waitcnt vmcnt(8) lgkmcnt(0)
	s_barrier
	v_mfma_f32_16x16x32_bf16 v[130:133], v[138:141], v[190:193], v[130:133]
	v_mfma_f32_16x16x32_bf16 v[126:129], v[146:149], v[190:193], v[126:129]
	v_mfma_f32_16x16x32_bf16 v[114:117], v[138:141], v[204:207], v[114:117]
	v_mfma_f32_16x16x32_bf16 v[110:113], v[146:149], v[204:207], v[110:113]
	v_mfma_f32_16x16x32_bf16 v[94:97], v[138:141], v[214:217], v[94:97]
	v_mfma_f32_16x16x32_bf16 v[90:93], v[146:149], v[214:217], v[90:93]
	v_mfma_f32_16x16x32_bf16 v[78:81], v[138:141], v[222:225], v[78:81]
	v_mfma_f32_16x16x32_bf16 v[74:77], v[146:149], v[222:225], v[74:77]
	v_mfma_f32_16x16x32_bf16 v[130:133], v[142:145], v[194:197], v[130:133]
	v_mfma_f32_16x16x32_bf16 v[126:129], v[150:153], v[194:197], v[126:129]
	v_mfma_f32_16x16x32_bf16 v[114:117], v[142:145], v[208:211], v[114:117]
	v_mfma_f32_16x16x32_bf16 v[110:113], v[150:153], v[208:211], v[110:113]
	v_mfma_f32_16x16x32_bf16 v[94:97], v[142:145], v[218:221], v[94:97]
	v_mfma_f32_16x16x32_bf16 v[90:93], v[150:153], v[218:221], v[90:93]
	v_mfma_f32_16x16x32_bf16 v[78:81], v[142:145], v[226:229], v[78:81]
	v_mfma_f32_16x16x32_bf16 v[74:77], v[150:153], v[226:229], v[74:77]
	s_setprio 0
	s_setprio 1
	v_mfma_f32_16x16x32_bf16 v[122:125], v[154:157], v[190:193], v[122:125]
	v_mfma_f32_16x16x32_bf16 v[118:121], v[182:185], v[190:193], v[118:121]
	v_mfma_f32_16x16x32_bf16 v[106:109], v[154:157], v[204:207], v[106:109]
	v_mfma_f32_16x16x32_bf16 v[100:103], v[182:185], v[204:207], v[102:105]
	v_mfma_f32_16x16x32_bf16 v[86:89], v[154:157], v[214:217], v[86:89]
	v_mfma_f32_16x16x32_bf16 v[82:85], v[182:185], v[214:217], v[82:85]
	v_mfma_f32_16x16x32_bf16 v[70:73], v[154:157], v[222:225], v[70:73]
	v_mfma_f32_16x16x32_bf16 v[66:69], v[182:185], v[222:225], v[66:69]
	v_mfma_f32_16x16x32_bf16 v[122:125], v[170:173], v[194:197], v[122:125]
	v_mfma_f32_16x16x32_bf16 v[118:121], v[186:189], v[194:197], v[118:121]
	v_mfma_f32_16x16x32_bf16 v[106:109], v[170:173], v[208:211], v[106:109]
	v_mfma_f32_16x16x32_bf16 v[100:103], v[186:189], v[208:211], v[100:103]
	v_mfma_f32_16x16x32_bf16 v[86:89], v[170:173], v[218:221], v[86:89]
	v_mfma_f32_16x16x32_bf16 v[82:85], v[186:189], v[218:221], v[82:85]
	v_mfma_f32_16x16x32_bf16 v[70:73], v[170:173], v[226:229], v[70:73]
	v_mfma_f32_16x16x32_bf16 v[66:69], v[186:189], v[226:229], v[66:69]
	s_setprio 0
	s_barrier
	s_add_i32 s76, s78, s9
	v_lshl_add_u64 v[174:175], s[60:61], 0, v[162:163]
	s_mov_b32 m0, s76
	ds_read_b128 v[190:193], v181 offset:16384
	ds_read_b128 v[194:197], v181 offset:17408
	ds_read_b128 v[204:207], v181 offset:18432
	ds_read_b128 v[208:211], v181 offset:19456
	ds_read_b128 v[214:217], v181 offset:20480
	ds_read_b128 v[218:221], v181 offset:21504
	ds_read_b128 v[222:225], v181 offset:22528
	ds_read_b128 v[226:229], v181 offset:23552
	s_setprio 1
	global_load_lds_dwordx4 v[174:175], off
	s_add_i32 m0, s76, 0x2000
	s_add_u32 s76, s60, 0x40000
	v_lshl_add_u64 v[198:199], s[60:61], 0, v[158:159]
	s_addc_u32 s77, s61, 0
	s_add_i32 s78, s79, s9
	global_load_lds_dwordx4 v[198:199], off
	v_lshl_add_u64 v[104:105], s[76:77], 0, v[162:163]
	s_mov_b32 m0, s78
	v_lshl_add_u64 v[230:231], s[62:63], 0, v[164:165]
	global_load_lds_dwordx4 v[104:105], off
	v_lshl_add_u64 v[104:105], s[76:77], 0, v[158:159]
	s_add_i32 m0, s78, 0x2000
	v_lshl_add_u64 v[232:233], s[62:63], 0, v[160:161]
	global_load_lds_dwordx4 v[104:105], off
	s_mov_b32 m0, s10
	s_nop 0
	global_load_lds_dwordx4 v[230:231], off
	s_mov_b32 m0, s11
	s_nop 0
	global_load_lds_dwordx4 v[232:233], off
	s_waitcnt vmcnt(8) lgkmcnt(0)
	s_barrier
	v_mfma_f32_16x16x32_bf16 v[62:65], v[138:141], v[190:193], v[62:65]
	v_mfma_f32_16x16x32_bf16 v[58:61], v[146:149], v[190:193], v[58:61]
	v_mfma_f32_16x16x32_bf16 v[46:49], v[138:141], v[204:207], v[46:49]
	v_mfma_f32_16x16x32_bf16 v[42:45], v[146:149], v[204:207], v[42:45]
	v_mfma_f32_16x16x32_bf16 v[30:33], v[138:141], v[214:217], v[30:33]
	v_mfma_f32_16x16x32_bf16 v[26:29], v[146:149], v[214:217], v[26:29]
	v_mfma_f32_16x16x32_bf16 v[14:17], v[138:141], v[222:225], v[14:17]
	v_mfma_f32_16x16x32_bf16 v[10:13], v[146:149], v[222:225], v[10:13]
	v_mfma_f32_16x16x32_bf16 v[62:65], v[142:145], v[194:197], v[62:65]
	v_mfma_f32_16x16x32_bf16 v[58:61], v[150:153], v[194:197], v[58:61]
	v_mfma_f32_16x16x32_bf16 v[46:49], v[142:145], v[208:211], v[46:49]
	v_mfma_f32_16x16x32_bf16 v[42:45], v[150:153], v[208:211], v[42:45]
	v_mfma_f32_16x16x32_bf16 v[30:33], v[142:145], v[218:221], v[30:33]
	v_mfma_f32_16x16x32_bf16 v[26:29], v[150:153], v[218:221], v[26:29]
	v_mfma_f32_16x16x32_bf16 v[14:17], v[142:145], v[226:229], v[14:17]
	v_mfma_f32_16x16x32_bf16 v[10:13], v[150:153], v[226:229], v[10:13]
	s_setprio 0
	s_setprio 1
	v_mfma_f32_16x16x32_bf16 v[54:57], v[154:157], v[190:193], v[54:57]
	v_mfma_f32_16x16x32_bf16 v[50:53], v[182:185], v[190:193], v[50:53]
	v_mfma_f32_16x16x32_bf16 v[38:41], v[154:157], v[204:207], v[38:41]
	v_mfma_f32_16x16x32_bf16 v[34:37], v[182:185], v[204:207], v[34:37]
	v_mfma_f32_16x16x32_bf16 v[22:25], v[154:157], v[214:217], v[22:25]
	v_mfma_f32_16x16x32_bf16 v[18:21], v[182:185], v[214:217], v[18:21]
	v_mfma_f32_16x16x32_bf16 v[6:9], v[154:157], v[222:225], v[6:9]
	v_mfma_f32_16x16x32_bf16 v[2:5], v[182:185], v[222:225], v[2:5]
	v_mfma_f32_16x16x32_bf16 v[54:57], v[170:173], v[194:197], v[54:57]
	v_mfma_f32_16x16x32_bf16 v[50:53], v[186:189], v[194:197], v[50:53]
	v_mfma_f32_16x16x32_bf16 v[38:41], v[170:173], v[208:211], v[38:41]
	v_mfma_f32_16x16x32_bf16 v[34:37], v[186:189], v[208:211], v[34:37]
	v_mfma_f32_16x16x32_bf16 v[22:25], v[170:173], v[218:221], v[22:25]
	v_mfma_f32_16x16x32_bf16 v[18:21], v[186:189], v[218:221], v[18:21]
	v_mfma_f32_16x16x32_bf16 v[6:9], v[170:173], v[226:229], v[6:9]
	v_mfma_f32_16x16x32_bf16 v[2:5], v[186:189], v[226:229], v[2:5]
	s_setprio 0
	s_barrier
	s_add_i32 s76, 0, 0x18000
	v_add_u32_e32 v98, s76, v177
	s_add_i32 s77, 0, 0x1c000
	ds_read_b128 v[138:141], v98
	ds_read_b128 v[142:145], v98 offset:1024
	ds_read_b128 v[146:149], v98 offset:2048
	ds_read_b128 v[150:153], v98 offset:3072
	v_add_u32_e32 v98, s77, v177
	ds_read_b128 v[154:157], v98
	ds_read_b128 v[170:173], v98 offset:1024
	ds_read_b128 v[182:185], v98 offset:2048
	ds_read_b128 v[186:189], v98 offset:3072
	s_add_u32 s62, s62, 0x40000
	s_addc_u32 s63, s63, 0
	s_mov_b32 m0, s12
	v_lshl_add_u64 v[104:105], s[62:63], 0, v[164:165]
	ds_read_b128 v[190:193], v181 offset:32768
	ds_read_b128 v[194:197], v181 offset:33792
	ds_read_b128 v[204:207], v181 offset:34816
	ds_read_b128 v[208:211], v181 offset:35840
	ds_read_b128 v[214:217], v181 offset:36864
	ds_read_b128 v[218:221], v181 offset:37888
	ds_read_b128 v[222:225], v181 offset:38912
	ds_read_b128 v[226:229], v181 offset:39936
	s_setprio 1
	global_load_lds_dwordx4 v[104:105], off
	v_lshl_add_u64 v[104:105], s[62:63], 0, v[160:161]
	s_mov_b32 m0, s13
	s_nop 0
	global_load_lds_dwordx4 v[104:105], off
	s_waitcnt vmcnt(8) lgkmcnt(0)
	s_barrier
	v_mfma_f32_16x16x32_bf16 v[130:133], v[138:141], v[190:193], v[130:133]
	v_mfma_f32_16x16x32_bf16 v[126:129], v[146:149], v[190:193], v[126:129]
	v_mfma_f32_16x16x32_bf16 v[114:117], v[138:141], v[204:207], v[114:117]
	v_mfma_f32_16x16x32_bf16 v[110:113], v[146:149], v[204:207], v[110:113]
	v_mfma_f32_16x16x32_bf16 v[94:97], v[138:141], v[214:217], v[94:97]
	v_mfma_f32_16x16x32_bf16 v[90:93], v[146:149], v[214:217], v[90:93]
	v_mfma_f32_16x16x32_bf16 v[78:81], v[138:141], v[222:225], v[78:81]
	v_mfma_f32_16x16x32_bf16 v[74:77], v[146:149], v[222:225], v[74:77]
	v_mfma_f32_16x16x32_bf16 v[130:133], v[142:145], v[194:197], v[130:133]
	v_mfma_f32_16x16x32_bf16 v[126:129], v[150:153], v[194:197], v[126:129]
	v_mfma_f32_16x16x32_bf16 v[114:117], v[142:145], v[208:211], v[114:117]
	v_mfma_f32_16x16x32_bf16 v[110:113], v[150:153], v[208:211], v[110:113]
	v_mfma_f32_16x16x32_bf16 v[94:97], v[142:145], v[218:221], v[94:97]
	v_mfma_f32_16x16x32_bf16 v[90:93], v[150:153], v[218:221], v[90:93]
	v_mfma_f32_16x16x32_bf16 v[78:81], v[142:145], v[226:229], v[78:81]
	v_mfma_f32_16x16x32_bf16 v[74:77], v[150:153], v[226:229], v[74:77]
	s_setprio 0
	s_setprio 1
	v_mfma_f32_16x16x32_bf16 v[122:125], v[154:157], v[190:193], v[122:125]
	v_mfma_f32_16x16x32_bf16 v[118:121], v[182:185], v[190:193], v[118:121]
	v_mfma_f32_16x16x32_bf16 v[104:107], v[154:157], v[204:207], v[106:109]
	v_mfma_f32_16x16x32_bf16 v[100:103], v[182:185], v[204:207], v[100:103]
	v_mfma_f32_16x16x32_bf16 v[86:89], v[154:157], v[214:217], v[86:89]
	v_mfma_f32_16x16x32_bf16 v[82:85], v[182:185], v[214:217], v[82:85]
	v_mfma_f32_16x16x32_bf16 v[70:73], v[154:157], v[222:225], v[70:73]
	v_mfma_f32_16x16x32_bf16 v[66:69], v[182:185], v[222:225], v[66:69]
	v_mfma_f32_16x16x32_bf16 v[122:125], v[170:173], v[194:197], v[122:125]
	v_mfma_f32_16x16x32_bf16 v[118:121], v[186:189], v[194:197], v[118:121]
	v_mfma_f32_16x16x32_bf16 v[106:109], v[170:173], v[208:211], v[104:107]
	v_mfma_f32_16x16x32_bf16 v[102:105], v[186:189], v[208:211], v[100:103]
	v_mfma_f32_16x16x32_bf16 v[86:89], v[170:173], v[218:221], v[86:89]
	v_mfma_f32_16x16x32_bf16 v[82:85], v[186:189], v[218:221], v[82:85]
	v_mfma_f32_16x16x32_bf16 v[70:73], v[170:173], v[226:229], v[70:73]
	v_mfma_f32_16x16x32_bf16 v[66:69], v[186:189], v[226:229], v[66:69]
	s_setprio 0
	s_barrier
	s_add_i32 s62, s76, s9
	v_lshl_add_u64 v[100:101], v[174:175], 0, s[28:29]
	s_mov_b32 m0, s62
	ds_read_b128 v[190:193], v181 offset:49152
	ds_read_b128 v[194:197], v181 offset:50176
	ds_read_b128 v[204:207], v181 offset:51200
	ds_read_b128 v[208:211], v181 offset:52224
	ds_read_b128 v[214:217], v181 offset:53248
	ds_read_b128 v[218:221], v181 offset:54272
	ds_read_b128 v[222:225], v181 offset:55296
	ds_read_b128 v[226:229], v181 offset:56320
	s_setprio 1
	global_load_lds_dwordx4 v[100:101], off
	s_add_i32 m0, s62, 0x2000
	s_add_u32 s60, s60, 0x40080
	v_lshl_add_u64 v[100:101], v[198:199], 0, s[28:29]
	s_addc_u32 s61, s61, 0
	s_add_i32 s62, s77, s9
	global_load_lds_dwordx4 v[100:101], off
	v_lshl_add_u64 v[100:101], s[60:61], 0, v[162:163]
	s_mov_b32 m0, s62
	s_nop 0
	global_load_lds_dwordx4 v[100:101], off
	v_lshl_add_u64 v[100:101], s[60:61], 0, v[158:159]
	s_add_i32 m0, s62, 0x2000
	s_nop 0
	global_load_lds_dwordx4 v[100:101], off
	v_lshl_add_u64 v[100:101], v[230:231], 0, s[28:29]
	s_mov_b32 m0, s16
	s_nop 0
	global_load_lds_dwordx4 v[100:101], off
	v_lshl_add_u64 v[100:101], v[232:233], 0, s[28:29]
	s_mov_b32 m0, s17
	s_nop 0
	global_load_lds_dwordx4 v[100:101], off
	s_waitcnt vmcnt(8) lgkmcnt(0)
	s_barrier
	v_mfma_f32_16x16x32_bf16 v[62:65], v[138:141], v[190:193], v[62:65]
	v_mfma_f32_16x16x32_bf16 v[58:61], v[146:149], v[190:193], v[58:61]
	v_mfma_f32_16x16x32_bf16 v[46:49], v[138:141], v[204:207], v[46:49]
	v_mfma_f32_16x16x32_bf16 v[42:45], v[146:149], v[204:207], v[42:45]
	v_mfma_f32_16x16x32_bf16 v[30:33], v[138:141], v[214:217], v[30:33]
	v_mfma_f32_16x16x32_bf16 v[26:29], v[146:149], v[214:217], v[26:29]
	v_mfma_f32_16x16x32_bf16 v[14:17], v[138:141], v[222:225], v[14:17]
	v_mfma_f32_16x16x32_bf16 v[10:13], v[146:149], v[222:225], v[10:13]
	v_mfma_f32_16x16x32_bf16 v[62:65], v[142:145], v[194:197], v[62:65]
	v_mfma_f32_16x16x32_bf16 v[58:61], v[150:153], v[194:197], v[58:61]
	v_mfma_f32_16x16x32_bf16 v[46:49], v[142:145], v[208:211], v[46:49]
	v_mfma_f32_16x16x32_bf16 v[42:45], v[150:153], v[208:211], v[42:45]
	v_mfma_f32_16x16x32_bf16 v[30:33], v[142:145], v[218:221], v[30:33]
	v_mfma_f32_16x16x32_bf16 v[26:29], v[150:153], v[218:221], v[26:29]
	v_mfma_f32_16x16x32_bf16 v[14:17], v[142:145], v[226:229], v[14:17]
	v_mfma_f32_16x16x32_bf16 v[10:13], v[150:153], v[226:229], v[10:13]
	s_setprio 0
	s_setprio 1
	v_mfma_f32_16x16x32_bf16 v[54:57], v[154:157], v[190:193], v[54:57]
	v_mfma_f32_16x16x32_bf16 v[50:53], v[182:185], v[190:193], v[50:53]
	v_mfma_f32_16x16x32_bf16 v[38:41], v[154:157], v[204:207], v[38:41]
	v_mfma_f32_16x16x32_bf16 v[34:37], v[182:185], v[204:207], v[34:37]
	v_mfma_f32_16x16x32_bf16 v[22:25], v[154:157], v[214:217], v[22:25]
	v_mfma_f32_16x16x32_bf16 v[18:21], v[182:185], v[214:217], v[18:21]
	v_mfma_f32_16x16x32_bf16 v[6:9], v[154:157], v[222:225], v[6:9]
	v_mfma_f32_16x16x32_bf16 v[2:5], v[182:185], v[222:225], v[2:5]
	v_mfma_f32_16x16x32_bf16 v[54:57], v[170:173], v[194:197], v[54:57]
	v_mfma_f32_16x16x32_bf16 v[50:53], v[186:189], v[194:197], v[50:53]
	v_mfma_f32_16x16x32_bf16 v[38:41], v[170:173], v[208:211], v[38:41]
	v_mfma_f32_16x16x32_bf16 v[34:37], v[186:189], v[208:211], v[34:37]
	v_mfma_f32_16x16x32_bf16 v[22:25], v[170:173], v[218:221], v[22:25]
	v_mfma_f32_16x16x32_bf16 v[18:21], v[186:189], v[218:221], v[18:21]
	v_mfma_f32_16x16x32_bf16 v[6:9], v[170:173], v[226:229], v[6:9]
	v_mfma_f32_16x16x32_bf16 v[2:5], v[186:189], v[226:229], v[2:5]
	s_setprio 0
	s_barrier
	s_add_u32 s58, s58, 0x100
	s_addc_u32 s59, s59, 0
	s_cmp_ge_u32 s75, s57
	s_cbranch_scc1 .LBB0_1113

.LBB0_1328:
	s_add_u32 s44, s42, 0xfffc0080
	s_addc_u32 s45, s43, -1
	s_add_i32 s53, 0, 0x10000
	s_cmp_eq_u32 s52, 12
	s_cselect_b32 s47, s1, s45
	s_cselect_b32 s46, s41, s44
	s_cselect_b32 s45, s48, s51
	s_cselect_b32 s44, s49, s50
	s_add_i32 s56, 0, 0x14000
	v_add_u32_e32 v94, s53, v186
	v_add_u32_e32 v174, s56, v186
	ds_read_b128 v[82:85], v94
	ds_read_b128 v[86:89], v94 offset:1024
	ds_read_b128 v[90:93], v94 offset:2048
	ds_read_b128 v[94:97], v94 offset:3072
	ds_read_b128 v[162:165], v174
	ds_read_b128 v[166:169], v174 offset:1024
	ds_read_b128 v[170:173], v174 offset:2048
	ds_read_b128 v[174:177], v174 offset:3072
	s_add_u32 s100, s42, 0xfffc0000
	s_addc_u32 s101, s43, -1
	v_lshl_add_u64 v[198:199], s[100:101], 0, v[148:149]
	s_mov_b32 m0, s33
	s_nop 0
	s_setprio 1
	global_load_lds_dwordx4 v[198:199], off
	v_lshl_add_u64 v[198:199], s[100:101], 0, v[150:151]
	s_mov_b32 m0, s14
	s_nop 0
	global_load_lds_dwordx4 v[198:199], off
	v_lshl_add_u64 v[198:199], s[42:43], 0, v[158:159]
	s_add_i32 m0, s2, 0xc000
	ds_read_b128 v[178:181], v187
	ds_read_b128 v[182:185], v187 offset:1024
	ds_read_b128 v[190:193], v187 offset:2048
	ds_read_b128 v[194:197], v187 offset:3072
	ds_read_b128 v[204:207], v187 offset:4096
	ds_read_b128 v[208:211], v187 offset:5120
	ds_read_b128 v[214:217], v187 offset:6144
	ds_read_b128 v[218:221], v187 offset:7168
	global_load_lds_dwordx4 v[198:199], off
	v_lshl_add_u64 v[198:199], s[42:43], 0, v[160:161]
	s_add_i32 m0, s2, 0xe000
	s_nop 0
	global_load_lds_dwordx4 v[198:199], off
	s_waitcnt vmcnt(8) lgkmcnt(0)
	s_barrier
	v_mfma_f32_16x16x32_bf16 v[144:147], v[82:85], v[178:181], v[144:147]
	v_mfma_f32_16x16x32_bf16 v[140:143], v[90:93], v[178:181], v[140:143]
	v_mfma_f32_16x16x32_bf16 v[128:131], v[82:85], v[190:193], v[128:131]
	v_mfma_f32_16x16x32_bf16 v[124:127], v[90:93], v[190:193], v[124:127]
	v_mfma_f32_16x16x32_bf16 v[112:115], v[82:85], v[204:207], v[112:115]
	v_mfma_f32_16x16x32_bf16 v[108:111], v[90:93], v[204:207], v[108:111]
	v_mfma_f32_16x16x32_bf16 v[78:81], v[82:85], v[214:217], v[78:81]
	v_mfma_f32_16x16x32_bf16 v[74:77], v[90:93], v[214:217], v[74:77]
	v_mfma_f32_16x16x32_bf16 v[144:147], v[86:89], v[182:185], v[144:147]
	v_mfma_f32_16x16x32_bf16 v[140:143], v[94:97], v[182:185], v[140:143]
	v_mfma_f32_16x16x32_bf16 v[128:131], v[86:89], v[194:197], v[128:131]
	v_mfma_f32_16x16x32_bf16 v[124:127], v[94:97], v[194:197], v[124:127]
	v_mfma_f32_16x16x32_bf16 v[112:115], v[86:89], v[208:211], v[112:115]
	v_mfma_f32_16x16x32_bf16 v[108:111], v[94:97], v[208:211], v[108:111]
	v_mfma_f32_16x16x32_bf16 v[78:81], v[86:89], v[218:221], v[78:81]
	v_mfma_f32_16x16x32_bf16 v[74:77], v[94:97], v[218:221], v[74:77]
	s_setprio 0
	s_setprio 1
	v_mfma_f32_16x16x32_bf16 v[136:139], v[162:165], v[178:181], v[136:139]
	v_mfma_f32_16x16x32_bf16 v[132:135], v[170:173], v[178:181], v[132:135]
	v_mfma_f32_16x16x32_bf16 v[120:123], v[162:165], v[190:193], v[120:123]
	v_mfma_f32_16x16x32_bf16 v[116:119], v[170:173], v[190:193], v[116:119]
	v_mfma_f32_16x16x32_bf16 v[104:107], v[162:165], v[204:207], v[104:107]
	v_mfma_f32_16x16x32_bf16 v[100:103], v[170:173], v[204:207], v[100:103]
	v_mfma_f32_16x16x32_bf16 v[70:73], v[162:165], v[214:217], v[70:73]
	v_mfma_f32_16x16x32_bf16 v[66:69], v[170:173], v[214:217], v[66:69]
	v_mfma_f32_16x16x32_bf16 v[136:139], v[166:169], v[182:185], v[136:139]
	v_mfma_f32_16x16x32_bf16 v[132:135], v[174:177], v[182:185], v[132:135]
	v_mfma_f32_16x16x32_bf16 v[120:123], v[166:169], v[194:197], v[120:123]
	v_mfma_f32_16x16x32_bf16 v[116:119], v[174:177], v[194:197], v[116:119]
	v_mfma_f32_16x16x32_bf16 v[104:107], v[166:169], v[208:211], v[104:107]
	v_mfma_f32_16x16x32_bf16 v[100:103], v[174:177], v[208:211], v[100:103]
	v_mfma_f32_16x16x32_bf16 v[70:73], v[166:169], v[218:221], v[70:73]
	v_mfma_f32_16x16x32_bf16 v[66:69], v[174:177], v[218:221], v[66:69]
	s_setprio 0
	s_barrier
	s_add_i32 s53, s53, s9
	v_lshl_add_u64 v[198:199], s[44:45], 0, v[98:99]
	s_mov_b32 m0, s53
	ds_read_b128 v[178:181], v187 offset:16384
	ds_read_b128 v[182:185], v187 offset:17408
	ds_read_b128 v[190:193], v187 offset:18432
	ds_read_b128 v[194:197], v187 offset:19456
	ds_read_b128 v[204:207], v187 offset:20480
	ds_read_b128 v[208:211], v187 offset:21504
	ds_read_b128 v[214:217], v187 offset:22528
	ds_read_b128 v[218:221], v187 offset:23552
	s_setprio 1
	global_load_lds_dwordx4 v[198:199], off
	s_add_i32 m0, s53, 0x2000
	s_add_u32 s54, s44, 0x40000
	v_lshl_add_u64 v[222:223], s[44:45], 0, v[152:153]
	s_addc_u32 s55, s45, 0
	s_add_i32 s53, s56, s9
	global_load_lds_dwordx4 v[222:223], off
	v_lshl_add_u64 v[224:225], s[54:55], 0, v[98:99]
	s_mov_b32 m0, s53
	s_nop 0
	global_load_lds_dwordx4 v[224:225], off
	v_lshl_add_u64 v[224:225], s[54:55], 0, v[152:153]
	s_add_i32 m0, s53, 0x2000
	s_nop 0
	global_load_lds_dwordx4 v[224:225], off
	s_waitcnt vmcnt(6) lgkmcnt(0)
	s_barrier
	v_mfma_f32_16x16x32_bf16 v[62:65], v[82:85], v[178:181], v[62:65]
	v_mfma_f32_16x16x32_bf16 v[58:61], v[90:93], v[178:181], v[58:61]
	v_mfma_f32_16x16x32_bf16 v[46:49], v[82:85], v[190:193], v[46:49]
	v_mfma_f32_16x16x32_bf16 v[42:45], v[90:93], v[190:193], v[42:45]
	v_mfma_f32_16x16x32_bf16 v[30:33], v[82:85], v[204:207], v[30:33]
	v_mfma_f32_16x16x32_bf16 v[26:29], v[90:93], v[204:207], v[26:29]
	v_mfma_f32_16x16x32_bf16 v[14:17], v[82:85], v[214:217], v[14:17]
	v_mfma_f32_16x16x32_bf16 v[10:13], v[90:93], v[214:217], v[10:13]
	v_mfma_f32_16x16x32_bf16 v[62:65], v[86:89], v[182:185], v[62:65]
	v_mfma_f32_16x16x32_bf16 v[58:61], v[94:97], v[182:185], v[58:61]
	v_mfma_f32_16x16x32_bf16 v[46:49], v[86:89], v[194:197], v[46:49]
	v_mfma_f32_16x16x32_bf16 v[42:45], v[94:97], v[194:197], v[42:45]
	v_mfma_f32_16x16x32_bf16 v[30:33], v[86:89], v[208:211], v[30:33]
	v_mfma_f32_16x16x32_bf16 v[26:29], v[94:97], v[208:211], v[26:29]
	v_mfma_f32_16x16x32_bf16 v[14:17], v[86:89], v[218:221], v[14:17]
	v_mfma_f32_16x16x32_bf16 v[10:13], v[94:97], v[218:221], v[10:13]
	s_setprio 0
	s_setprio 1
	v_mfma_f32_16x16x32_bf16 v[54:57], v[162:165], v[178:181], v[54:57]
	v_mfma_f32_16x16x32_bf16 v[50:53], v[170:173], v[178:181], v[50:53]
	v_mfma_f32_16x16x32_bf16 v[38:41], v[162:165], v[190:193], v[38:41]
	v_mfma_f32_16x16x32_bf16 v[34:37], v[170:173], v[190:193], v[34:37]
	v_mfma_f32_16x16x32_bf16 v[22:25], v[162:165], v[204:207], v[22:25]
	v_mfma_f32_16x16x32_bf16 v[18:21], v[170:173], v[204:207], v[18:21]
	v_mfma_f32_16x16x32_bf16 v[6:9], v[162:165], v[214:217], v[6:9]
	v_mfma_f32_16x16x32_bf16 v[2:5], v[170:173], v[214:217], v[2:5]
	v_mfma_f32_16x16x32_bf16 v[54:57], v[166:169], v[182:185], v[54:57]
	v_mfma_f32_16x16x32_bf16 v[50:53], v[174:177], v[182:185], v[50:53]
	v_mfma_f32_16x16x32_bf16 v[38:41], v[166:169], v[194:197], v[38:41]
	v_mfma_f32_16x16x32_bf16 v[34:37], v[174:177], v[194:197], v[34:37]
	v_mfma_f32_16x16x32_bf16 v[22:25], v[166:169], v[208:211], v[22:25]
	v_mfma_f32_16x16x32_bf16 v[18:21], v[174:177], v[208:211], v[18:21]
	v_mfma_f32_16x16x32_bf16 v[6:9], v[166:169], v[218:221], v[6:9]
	v_mfma_f32_16x16x32_bf16 v[2:5], v[174:177], v[218:221], v[2:5]
	s_setprio 0
	s_barrier
	s_add_i32 s53, 0, 0x18000
	s_add_i32 s54, 0, 0x1c000
	v_add_u32_e32 v94, s53, v186
	v_add_u32_e32 v174, s54, v186
	ds_read_b128 v[82:85], v94
	ds_read_b128 v[86:89], v94 offset:1024
	ds_read_b128 v[90:93], v94 offset:2048
	ds_read_b128 v[94:97], v94 offset:3072
	ds_read_b128 v[162:165], v174
	ds_read_b128 v[166:169], v174 offset:1024
	ds_read_b128 v[170:173], v174 offset:2048
	ds_read_b128 v[174:177], v174 offset:3072
	v_lshl_add_u64 v[224:225], s[46:47], 0, v[148:149]
	s_mov_b32 m0, s2
	v_lshl_add_u64 v[226:227], s[46:47], 0, v[150:151]
	s_setprio 1
	global_load_lds_dwordx4 v[224:225], off
	s_mov_b32 m0, s4
	s_nop 0
	global_load_lds_dwordx4 v[226:227], off
	s_add_u32 s46, s46, 0x40000
	s_addc_u32 s47, s47, 0
	s_mov_b32 m0, s12
	v_lshl_add_u64 v[228:229], s[46:47], 0, v[148:149]
	ds_read_b128 v[178:181], v187 offset:32768
	ds_read_b128 v[182:185], v187 offset:33792
	ds_read_b128 v[190:193], v187 offset:34816
	ds_read_b128 v[194:197], v187 offset:35840
	ds_read_b128 v[204:207], v187 offset:36864
	ds_read_b128 v[208:211], v187 offset:37888
	ds_read_b128 v[214:217], v187 offset:38912
	ds_read_b128 v[218:221], v187 offset:39936
	global_load_lds_dwordx4 v[228:229], off
	v_lshl_add_u64 v[228:229], s[46:47], 0, v[150:151]
	s_mov_b32 m0, s13
	s_nop 0
	global_load_lds_dwordx4 v[228:229], off
	s_waitcnt vmcnt(8) lgkmcnt(0)
	s_barrier
	v_mfma_f32_16x16x32_bf16 v[144:147], v[82:85], v[178:181], v[144:147]
	v_mfma_f32_16x16x32_bf16 v[140:143], v[90:93], v[178:181], v[140:143]
	v_mfma_f32_16x16x32_bf16 v[128:131], v[82:85], v[190:193], v[128:131]
	v_mfma_f32_16x16x32_bf16 v[124:127], v[90:93], v[190:193], v[124:127]
	v_mfma_f32_16x16x32_bf16 v[112:115], v[82:85], v[204:207], v[112:115]
	v_mfma_f32_16x16x32_bf16 v[108:111], v[90:93], v[204:207], v[108:111]
	v_mfma_f32_16x16x32_bf16 v[78:81], v[82:85], v[214:217], v[78:81]
	v_mfma_f32_16x16x32_bf16 v[74:77], v[90:93], v[214:217], v[74:77]
	v_mfma_f32_16x16x32_bf16 v[144:147], v[86:89], v[182:185], v[144:147]
	v_mfma_f32_16x16x32_bf16 v[140:143], v[94:97], v[182:185], v[140:143]
	v_mfma_f32_16x16x32_bf16 v[128:131], v[86:89], v[194:197], v[128:131]
	v_mfma_f32_16x16x32_bf16 v[124:127], v[94:97], v[194:197], v[124:127]
	v_mfma_f32_16x16x32_bf16 v[112:115], v[86:89], v[208:211], v[112:115]
	v_mfma_f32_16x16x32_bf16 v[108:111], v[94:97], v[208:211], v[108:111]
	v_mfma_f32_16x16x32_bf16 v[78:81], v[86:89], v[218:221], v[78:81]
	v_mfma_f32_16x16x32_bf16 v[74:77], v[94:97], v[218:221], v[74:77]
	s_setprio 0
	s_setprio 1
	v_mfma_f32_16x16x32_bf16 v[136:139], v[162:165], v[178:181], v[136:139]
	v_mfma_f32_16x16x32_bf16 v[132:135], v[170:173], v[178:181], v[132:135]
	v_mfma_f32_16x16x32_bf16 v[120:123], v[162:165], v[190:193], v[120:123]
	v_mfma_f32_16x16x32_bf16 v[116:119], v[170:173], v[190:193], v[116:119]
	v_mfma_f32_16x16x32_bf16 v[104:107], v[162:165], v[204:207], v[104:107]
	v_mfma_f32_16x16x32_bf16 v[100:103], v[170:173], v[204:207], v[100:103]
	v_mfma_f32_16x16x32_bf16 v[70:73], v[162:165], v[214:217], v[70:73]
	v_mfma_f32_16x16x32_bf16 v[66:69], v[170:173], v[214:217], v[66:69]
	v_mfma_f32_16x16x32_bf16 v[136:139], v[166:169], v[182:185], v[136:139]
	v_mfma_f32_16x16x32_bf16 v[132:135], v[174:177], v[182:185], v[132:135]
	v_mfma_f32_16x16x32_bf16 v[120:123], v[166:169], v[194:197], v[120:123]
	v_mfma_f32_16x16x32_bf16 v[116:119], v[174:177], v[194:197], v[116:119]
	v_mfma_f32_16x16x32_bf16 v[104:107], v[166:169], v[208:211], v[104:107]
	v_mfma_f32_16x16x32_bf16 v[100:103], v[174:177], v[208:211], v[100:103]
	v_mfma_f32_16x16x32_bf16 v[70:73], v[166:169], v[218:221], v[70:73]
	v_mfma_f32_16x16x32_bf16 v[66:69], v[174:177], v[218:221], v[66:69]
	s_setprio 0
	s_barrier
	s_add_i32 s46, s53, s9
	v_lshl_add_u64 v[198:199], v[198:199], 0, s[28:29]
	s_mov_b32 m0, s46
	ds_read_b128 v[178:181], v187 offset:49152
	ds_read_b128 v[182:185], v187 offset:50176
	ds_read_b128 v[190:193], v187 offset:51200
	ds_read_b128 v[194:197], v187 offset:52224
	ds_read_b128 v[204:207], v187 offset:53248
	ds_read_b128 v[208:211], v187 offset:54272
	ds_read_b128 v[214:217], v187 offset:55296
	ds_read_b128 v[218:221], v187 offset:56320
	s_setprio 1
	global_load_lds_dwordx4 v[198:199], off
	s_add_i32 m0, s46, 0x2000
	s_add_u32 s44, s44, 0x40080
	v_lshl_add_u64 v[198:199], v[222:223], 0, s[28:29]
	s_addc_u32 s45, s45, 0
	s_add_i32 s46, s54, s9
	global_load_lds_dwordx4 v[198:199], off
	v_lshl_add_u64 v[198:199], s[44:45], 0, v[98:99]
	s_mov_b32 m0, s46
	s_nop 0
	global_load_lds_dwordx4 v[198:199], off
	v_lshl_add_u64 v[198:199], s[44:45], 0, v[152:153]
	s_add_i32 m0, s46, 0x2000
	s_nop 0
	global_load_lds_dwordx4 v[198:199], off
	s_waitcnt vmcnt(6) lgkmcnt(0)
	s_barrier
	v_mfma_f32_16x16x32_bf16 v[62:65], v[82:85], v[178:181], v[62:65]
	v_mfma_f32_16x16x32_bf16 v[58:61], v[90:93], v[178:181], v[58:61]
	v_mfma_f32_16x16x32_bf16 v[46:49], v[82:85], v[190:193], v[46:49]
	v_mfma_f32_16x16x32_bf16 v[42:45], v[90:93], v[190:193], v[42:45]
	v_mfma_f32_16x16x32_bf16 v[30:33], v[82:85], v[204:207], v[30:33]
	v_mfma_f32_16x16x32_bf16 v[26:29], v[90:93], v[204:207], v[26:29]
	v_mfma_f32_16x16x32_bf16 v[14:17], v[82:85], v[214:217], v[14:17]
	v_mfma_f32_16x16x32_bf16 v[10:13], v[90:93], v[214:217], v[10:13]
	v_mfma_f32_16x16x32_bf16 v[62:65], v[86:89], v[182:185], v[62:65]
	v_mfma_f32_16x16x32_bf16 v[58:61], v[94:97], v[182:185], v[58:61]
	v_mfma_f32_16x16x32_bf16 v[46:49], v[86:89], v[194:197], v[46:49]
	v_mfma_f32_16x16x32_bf16 v[42:45], v[94:97], v[194:197], v[42:45]
	v_mfma_f32_16x16x32_bf16 v[30:33], v[86:89], v[208:211], v[30:33]
	v_mfma_f32_16x16x32_bf16 v[26:29], v[94:97], v[208:211], v[26:29]
	v_mfma_f32_16x16x32_bf16 v[14:17], v[86:89], v[218:221], v[14:17]
	v_mfma_f32_16x16x32_bf16 v[10:13], v[94:97], v[218:221], v[10:13]
	s_setprio 0
	s_setprio 1
	v_mfma_f32_16x16x32_bf16 v[54:57], v[162:165], v[178:181], v[54:57]
	v_mfma_f32_16x16x32_bf16 v[50:53], v[170:173], v[178:181], v[50:53]
	v_mfma_f32_16x16x32_bf16 v[38:41], v[162:165], v[190:193], v[38:41]
	v_mfma_f32_16x16x32_bf16 v[34:37], v[170:173], v[190:193], v[34:37]
	v_mfma_f32_16x16x32_bf16 v[22:25], v[162:165], v[204:207], v[22:25]
	v_mfma_f32_16x16x32_bf16 v[18:21], v[170:173], v[204:207], v[18:21]
	v_mfma_f32_16x16x32_bf16 v[6:9], v[162:165], v[214:217], v[6:9]
	v_mfma_f32_16x16x32_bf16 v[2:5], v[170:173], v[214:217], v[2:5]
	v_mfma_f32_16x16x32_bf16 v[54:57], v[166:169], v[182:185], v[54:57]
	v_mfma_f32_16x16x32_bf16 v[50:53], v[174:177], v[182:185], v[50:53]
	v_mfma_f32_16x16x32_bf16 v[38:41], v[166:169], v[194:197], v[38:41]
	v_mfma_f32_16x16x32_bf16 v[34:37], v[174:177], v[194:197], v[34:37]
	v_mfma_f32_16x16x32_bf16 v[22:25], v[166:169], v[208:211], v[22:25]
	v_mfma_f32_16x16x32_bf16 v[18:21], v[174:177], v[208:211], v[18:21]
	v_mfma_f32_16x16x32_bf16 v[6:9], v[166:169], v[218:221], v[6:9]
	v_mfma_f32_16x16x32_bf16 v[2:5], v[174:177], v[218:221], v[2:5]
	s_setprio 0
	s_barrier
	s_add_i32 s52, s52, 2
	s_add_u32 s42, s42, 0x100
	s_addc_u32 s43, s43, 0
	s_add_u32 s50, s50, 0x100
	s_addc_u32 s51, s51, 0
	s_cmp_gt_u32 s52, 13
	s_cbranch_scc0 .LBB0_1328
	s_and_b64 vcc, exec, s[76:77]
	s_cbranch_vccz .LBB0_1331
	s_barrier

.LBB0_1529:
	s_add_u32 s50, s48, 0x100
	s_addc_u32 s51, s49, 0
	s_add_i32 s58, 0, 0x10000
	s_cmp_eq_u32 s57, 40
	s_cselect_b32 s55, s1, s51
	s_cselect_b32 s54, s0, s50
	s_cselect_b32 s53, s47, s56
	s_cselect_b32 s52, s46, s33
	s_add_i32 s59, 0, 0x14000
	v_add_u32_e32 v144, s58, v186
	v_add_u32_e32 v160, s59, v186
	ds_read_b128 v[132:135], v144
	ds_read_b128 v[136:139], v144 offset:1024
	ds_read_b128 v[140:143], v144 offset:2048
	ds_read_b128 v[144:147], v144 offset:3072
	ds_read_b128 v[148:151], v160
	ds_read_b128 v[152:155], v160 offset:1024
	ds_read_b128 v[156:159], v160 offset:2048
	ds_read_b128 v[160:163], v160 offset:3072
	v_lshl_add_u64 v[214:215], s[48:49], 0, v[174:175]
	s_add_i32 m0, s4, 0xc000
	ds_read_b128 v[164:167], v187
	ds_read_b128 v[178:181], v187 offset:1024
	ds_read_b128 v[182:185], v187 offset:2048
	ds_read_b128 v[188:191], v187 offset:3072
	ds_read_b128 v[192:195], v187 offset:4096
	ds_read_b128 v[196:199], v187 offset:5120
	ds_read_b128 v[204:207], v187 offset:6144
	ds_read_b128 v[208:211], v187 offset:7168
	s_setprio 1
	global_load_lds_dwordx4 v[214:215], off
	v_lshl_add_u64 v[214:215], s[48:49], 0, v[176:177]
	s_add_i32 m0, s4, 0xe000
	s_nop 0
	global_load_lds_dwordx4 v[214:215], off
	s_waitcnt vmcnt(8) lgkmcnt(0)
	s_barrier
	v_mfma_f32_16x16x32_bf16 v[128:131], v[132:135], v[164:167], v[128:131]
	v_mfma_f32_16x16x32_bf16 v[124:127], v[140:143], v[164:167], v[124:127]
	v_mfma_f32_16x16x32_bf16 v[120:123], v[132:135], v[182:185], v[120:123]
	v_mfma_f32_16x16x32_bf16 v[116:119], v[140:143], v[182:185], v[116:119]
	v_mfma_f32_16x16x32_bf16 v[112:115], v[132:135], v[192:195], v[112:115]
	v_mfma_f32_16x16x32_bf16 v[108:111], v[140:143], v[192:195], v[108:111]
	v_mfma_f32_16x16x32_bf16 v[104:107], v[132:135], v[204:207], v[104:107]
	v_mfma_f32_16x16x32_bf16 v[100:103], v[140:143], v[204:207], v[100:103]
	v_mfma_f32_16x16x32_bf16 v[128:131], v[136:139], v[178:181], v[128:131]
	v_mfma_f32_16x16x32_bf16 v[124:127], v[144:147], v[178:181], v[124:127]
	v_mfma_f32_16x16x32_bf16 v[120:123], v[136:139], v[188:191], v[120:123]
	v_mfma_f32_16x16x32_bf16 v[116:119], v[144:147], v[188:191], v[116:119]
	v_mfma_f32_16x16x32_bf16 v[112:115], v[136:139], v[196:199], v[112:115]
	v_mfma_f32_16x16x32_bf16 v[108:111], v[144:147], v[196:199], v[108:111]
	v_mfma_f32_16x16x32_bf16 v[104:107], v[136:139], v[208:211], v[104:107]
	v_mfma_f32_16x16x32_bf16 v[100:103], v[144:147], v[208:211], v[100:103]
	s_setprio 0
	s_setprio 1
	v_mfma_f32_16x16x32_bf16 v[62:65], v[148:151], v[164:167], v[62:65]
	v_mfma_f32_16x16x32_bf16 v[58:61], v[156:159], v[164:167], v[58:61]
	v_mfma_f32_16x16x32_bf16 v[54:57], v[148:151], v[182:185], v[54:57]
	v_mfma_f32_16x16x32_bf16 v[50:53], v[156:159], v[182:185], v[50:53]
	v_mfma_f32_16x16x32_bf16 v[46:49], v[148:151], v[192:195], v[46:49]
	v_mfma_f32_16x16x32_bf16 v[42:45], v[156:159], v[192:195], v[42:45]
	v_mfma_f32_16x16x32_bf16 v[38:41], v[148:151], v[204:207], v[38:41]
	v_mfma_f32_16x16x32_bf16 v[34:37], v[156:159], v[204:207], v[34:37]
	v_mfma_f32_16x16x32_bf16 v[62:65], v[152:155], v[178:181], v[62:65]
	v_mfma_f32_16x16x32_bf16 v[58:61], v[160:163], v[178:181], v[58:61]
	v_mfma_f32_16x16x32_bf16 v[54:57], v[152:155], v[188:191], v[54:57]
	v_mfma_f32_16x16x32_bf16 v[50:53], v[160:163], v[188:191], v[50:53]
	v_mfma_f32_16x16x32_bf16 v[46:49], v[152:155], v[196:199], v[46:49]
	v_mfma_f32_16x16x32_bf16 v[42:45], v[160:163], v[196:199], v[42:45]
	v_mfma_f32_16x16x32_bf16 v[38:41], v[152:155], v[208:211], v[38:41]
	v_mfma_f32_16x16x32_bf16 v[34:37], v[160:163], v[208:211], v[34:37]
	s_setprio 0
	s_barrier
	s_add_i32 s48, s58, s2
	v_lshl_add_u64 v[214:215], s[52:53], 0, v[98:99]
	s_mov_b32 m0, s48
	ds_read_b128 v[164:167], v187 offset:16384
	ds_read_b128 v[178:181], v187 offset:17408
	ds_read_b128 v[182:185], v187 offset:18432
	ds_read_b128 v[188:191], v187 offset:19456
	ds_read_b128 v[192:195], v187 offset:20480
	ds_read_b128 v[196:199], v187 offset:21504
	ds_read_b128 v[204:207], v187 offset:22528
	ds_read_b128 v[208:211], v187 offset:23552
	s_setprio 1
	global_load_lds_dwordx4 v[214:215], off
	s_add_i32 m0, s48, 0x2000
	s_add_u32 s48, s52, 0xb0000
	v_lshl_add_u64 v[216:217], s[52:53], 0, v[168:169]
	s_addc_u32 s49, s53, 0
	s_add_i32 s58, s59, s2
	global_load_lds_dwordx4 v[216:217], off
	v_lshl_add_u64 v[218:219], s[48:49], 0, v[98:99]
	s_mov_b32 m0, s58
	v_lshl_add_u64 v[220:221], s[54:55], 0, v[170:171]
	global_load_lds_dwordx4 v[218:219], off
	v_lshl_add_u64 v[218:219], s[48:49], 0, v[168:169]
	s_add_i32 m0, s58, 0x2000
	s_nop 0
	global_load_lds_dwordx4 v[218:219], off
	v_lshl_add_u64 v[218:219], s[54:55], 0, v[172:173]
	s_mov_b32 m0, s4
	s_nop 0
	global_load_lds_dwordx4 v[218:219], off
	s_mov_b32 m0, s7
	s_nop 0
	global_load_lds_dwordx4 v[220:221], off
	s_waitcnt vmcnt(8) lgkmcnt(0)
	s_barrier
	v_mfma_f32_16x16x32_bf16 v[94:97], v[132:135], v[164:167], v[94:97]
	v_mfma_f32_16x16x32_bf16 v[90:93], v[140:143], v[164:167], v[90:93]
	v_mfma_f32_16x16x32_bf16 v[86:89], v[132:135], v[182:185], v[86:89]
	v_mfma_f32_16x16x32_bf16 v[82:85], v[140:143], v[182:185], v[82:85]
	v_mfma_f32_16x16x32_bf16 v[78:81], v[132:135], v[192:195], v[78:81]
	v_mfma_f32_16x16x32_bf16 v[74:77], v[140:143], v[192:195], v[74:77]
	v_mfma_f32_16x16x32_bf16 v[70:73], v[132:135], v[204:207], v[70:73]
	v_mfma_f32_16x16x32_bf16 v[66:69], v[140:143], v[204:207], v[66:69]
	v_mfma_f32_16x16x32_bf16 v[94:97], v[136:139], v[178:181], v[94:97]
	v_mfma_f32_16x16x32_bf16 v[90:93], v[144:147], v[178:181], v[90:93]
	v_mfma_f32_16x16x32_bf16 v[86:89], v[136:139], v[188:191], v[86:89]
	v_mfma_f32_16x16x32_bf16 v[82:85], v[144:147], v[188:191], v[82:85]
	v_mfma_f32_16x16x32_bf16 v[78:81], v[136:139], v[196:199], v[78:81]
	v_mfma_f32_16x16x32_bf16 v[74:77], v[144:147], v[196:199], v[74:77]
	v_mfma_f32_16x16x32_bf16 v[70:73], v[136:139], v[208:211], v[70:73]
	v_mfma_f32_16x16x32_bf16 v[66:69], v[144:147], v[208:211], v[66:69]
	s_setprio 0
	s_setprio 1
	v_mfma_f32_16x16x32_bf16 v[30:33], v[148:151], v[164:167], v[30:33]
	v_mfma_f32_16x16x32_bf16 v[26:29], v[156:159], v[164:167], v[26:29]
	v_mfma_f32_16x16x32_bf16 v[22:25], v[148:151], v[182:185], v[22:25]
	v_mfma_f32_16x16x32_bf16 v[18:21], v[156:159], v[182:185], v[18:21]
	v_mfma_f32_16x16x32_bf16 v[14:17], v[148:151], v[192:195], v[14:17]
	v_mfma_f32_16x16x32_bf16 v[10:13], v[156:159], v[192:195], v[10:13]
	v_mfma_f32_16x16x32_bf16 v[6:9], v[148:151], v[204:207], v[6:9]
	v_mfma_f32_16x16x32_bf16 v[2:5], v[156:159], v[204:207], v[2:5]
	v_mfma_f32_16x16x32_bf16 v[30:33], v[152:155], v[178:181], v[30:33]
	v_mfma_f32_16x16x32_bf16 v[26:29], v[160:163], v[178:181], v[26:29]
	v_mfma_f32_16x16x32_bf16 v[22:25], v[152:155], v[188:191], v[22:25]
	v_mfma_f32_16x16x32_bf16 v[18:21], v[160:163], v[188:191], v[18:21]
	v_mfma_f32_16x16x32_bf16 v[14:17], v[152:155], v[196:199], v[14:17]
	v_mfma_f32_16x16x32_bf16 v[10:13], v[160:163], v[196:199], v[10:13]
	v_mfma_f32_16x16x32_bf16 v[6:9], v[152:155], v[208:211], v[6:9]
	v_mfma_f32_16x16x32_bf16 v[2:5], v[160:163], v[208:211], v[2:5]
	s_setprio 0
	s_barrier
	s_add_i32 s58, 0, 0x18000
	s_add_i32 s59, 0, 0x1c000
	v_add_u32_e32 v144, s58, v186
	v_add_u32_e32 v160, s59, v186
	ds_read_b128 v[132:135], v144
	ds_read_b128 v[136:139], v144 offset:1024
	ds_read_b128 v[140:143], v144 offset:2048
	ds_read_b128 v[144:147], v144 offset:3072
	ds_read_b128 v[148:151], v160
	ds_read_b128 v[152:155], v160 offset:1024
	ds_read_b128 v[156:159], v160 offset:2048
	ds_read_b128 v[160:163], v160 offset:3072
	s_add_u32 s48, s54, 0xb0000
	s_addc_u32 s49, s55, 0
	s_mov_b32 m0, s8
	v_lshl_add_u64 v[222:223], s[48:49], 0, v[172:173]
	ds_read_b128 v[164:167], v187 offset:32768
	ds_read_b128 v[178:181], v187 offset:33792
	ds_read_b128 v[182:185], v187 offset:34816
	ds_read_b128 v[188:191], v187 offset:35840
	ds_read_b128 v[192:195], v187 offset:36864
	ds_read_b128 v[196:199], v187 offset:37888
	ds_read_b128 v[204:207], v187 offset:38912
	ds_read_b128 v[208:211], v187 offset:39936
	s_setprio 1
	global_load_lds_dwordx4 v[222:223], off
	v_lshl_add_u64 v[222:223], s[48:49], 0, v[170:171]
	s_mov_b32 m0, s9
	s_nop 0
	global_load_lds_dwordx4 v[222:223], off
	s_waitcnt vmcnt(8) lgkmcnt(0)
	s_barrier
	v_mfma_f32_16x16x32_bf16 v[128:131], v[132:135], v[164:167], v[128:131]
	v_mfma_f32_16x16x32_bf16 v[124:127], v[140:143], v[164:167], v[124:127]
	v_mfma_f32_16x16x32_bf16 v[120:123], v[132:135], v[182:185], v[120:123]
	v_mfma_f32_16x16x32_bf16 v[116:119], v[140:143], v[182:185], v[116:119]
	v_mfma_f32_16x16x32_bf16 v[112:115], v[132:135], v[192:195], v[112:115]
	v_mfma_f32_16x16x32_bf16 v[108:111], v[140:143], v[192:195], v[108:111]
	v_mfma_f32_16x16x32_bf16 v[104:107], v[132:135], v[204:207], v[104:107]
	v_mfma_f32_16x16x32_bf16 v[100:103], v[140:143], v[204:207], v[100:103]
	v_mfma_f32_16x16x32_bf16 v[128:131], v[136:139], v[178:181], v[128:131]
	v_mfma_f32_16x16x32_bf16 v[124:127], v[144:147], v[178:181], v[124:127]
	v_mfma_f32_16x16x32_bf16 v[120:123], v[136:139], v[188:191], v[120:123]
	v_mfma_f32_16x16x32_bf16 v[116:119], v[144:147], v[188:191], v[116:119]
	v_mfma_f32_16x16x32_bf16 v[112:115], v[136:139], v[196:199], v[112:115]
	v_mfma_f32_16x16x32_bf16 v[108:111], v[144:147], v[196:199], v[108:111]
	v_mfma_f32_16x16x32_bf16 v[104:107], v[136:139], v[208:211], v[104:107]
	v_mfma_f32_16x16x32_bf16 v[100:103], v[144:147], v[208:211], v[100:103]
	s_setprio 0
	s_setprio 1
	v_mfma_f32_16x16x32_bf16 v[62:65], v[148:151], v[164:167], v[62:65]
	v_mfma_f32_16x16x32_bf16 v[58:61], v[156:159], v[164:167], v[58:61]
	v_mfma_f32_16x16x32_bf16 v[54:57], v[148:151], v[182:185], v[54:57]
	v_mfma_f32_16x16x32_bf16 v[50:53], v[156:159], v[182:185], v[50:53]
	v_mfma_f32_16x16x32_bf16 v[46:49], v[148:151], v[192:195], v[46:49]
	v_mfma_f32_16x16x32_bf16 v[42:45], v[156:159], v[192:195], v[42:45]
	v_mfma_f32_16x16x32_bf16 v[38:41], v[148:151], v[204:207], v[38:41]
	v_mfma_f32_16x16x32_bf16 v[34:37], v[156:159], v[204:207], v[34:37]
	v_mfma_f32_16x16x32_bf16 v[62:65], v[152:155], v[178:181], v[62:65]
	v_mfma_f32_16x16x32_bf16 v[58:61], v[160:163], v[178:181], v[58:61]
	v_mfma_f32_16x16x32_bf16 v[54:57], v[152:155], v[188:191], v[54:57]
	v_mfma_f32_16x16x32_bf16 v[50:53], v[160:163], v[188:191], v[50:53]
	v_mfma_f32_16x16x32_bf16 v[46:49], v[152:155], v[196:199], v[46:49]
	v_mfma_f32_16x16x32_bf16 v[42:45], v[160:163], v[196:199], v[42:45]
	v_mfma_f32_16x16x32_bf16 v[38:41], v[152:155], v[208:211], v[38:41]
	v_mfma_f32_16x16x32_bf16 v[34:37], v[160:163], v[208:211], v[34:37]
	s_setprio 0
	s_barrier
	s_add_i32 s48, s58, s2
	v_lshl_add_u64 v[214:215], v[214:215], 0, s[28:29]
	s_mov_b32 m0, s48
	ds_read_b128 v[164:167], v187 offset:49152
	ds_read_b128 v[178:181], v187 offset:50176
	ds_read_b128 v[182:185], v187 offset:51200
	ds_read_b128 v[188:191], v187 offset:52224
	ds_read_b128 v[192:195], v187 offset:53248
	ds_read_b128 v[196:199], v187 offset:54272
	ds_read_b128 v[204:207], v187 offset:55296
	ds_read_b128 v[208:211], v187 offset:56320
	s_setprio 1
	global_load_lds_dwordx4 v[214:215], off
	s_add_i32 m0, s48, 0x2000
	s_add_u32 s48, s52, 0xb0080
	v_lshl_add_u64 v[214:215], v[216:217], 0, s[28:29]
	s_addc_u32 s49, s53, 0
	s_add_i32 s52, s59, s2
	global_load_lds_dwordx4 v[214:215], off
	v_lshl_add_u64 v[214:215], s[48:49], 0, v[98:99]
	s_mov_b32 m0, s52
	s_nop 0
	global_load_lds_dwordx4 v[214:215], off
	v_lshl_add_u64 v[214:215], s[48:49], 0, v[168:169]
	s_add_i32 m0, s52, 0x2000
	s_nop 0
	global_load_lds_dwordx4 v[214:215], off
	v_lshl_add_u64 v[214:215], v[218:219], 0, s[28:29]
	s_mov_b32 m0, s12
	s_nop 0
	global_load_lds_dwordx4 v[214:215], off
	v_lshl_add_u64 v[214:215], v[220:221], 0, s[28:29]
	s_mov_b32 m0, s13
	s_nop 0
	global_load_lds_dwordx4 v[214:215], off
	s_waitcnt vmcnt(8) lgkmcnt(0)
	s_barrier
	v_mfma_f32_16x16x32_bf16 v[94:97], v[132:135], v[164:167], v[94:97]
	v_mfma_f32_16x16x32_bf16 v[90:93], v[140:143], v[164:167], v[90:93]
	v_mfma_f32_16x16x32_bf16 v[86:89], v[132:135], v[182:185], v[86:89]
	v_mfma_f32_16x16x32_bf16 v[82:85], v[140:143], v[182:185], v[82:85]
	v_mfma_f32_16x16x32_bf16 v[78:81], v[132:135], v[192:195], v[78:81]
	v_mfma_f32_16x16x32_bf16 v[74:77], v[140:143], v[192:195], v[74:77]
	v_mfma_f32_16x16x32_bf16 v[70:73], v[132:135], v[204:207], v[70:73]
	v_mfma_f32_16x16x32_bf16 v[66:69], v[140:143], v[204:207], v[66:69]
	v_mfma_f32_16x16x32_bf16 v[94:97], v[136:139], v[178:181], v[94:97]
	v_mfma_f32_16x16x32_bf16 v[90:93], v[144:147], v[178:181], v[90:93]
	v_mfma_f32_16x16x32_bf16 v[86:89], v[136:139], v[188:191], v[86:89]
	v_mfma_f32_16x16x32_bf16 v[82:85], v[144:147], v[188:191], v[82:85]
	v_mfma_f32_16x16x32_bf16 v[78:81], v[136:139], v[196:199], v[78:81]
	v_mfma_f32_16x16x32_bf16 v[74:77], v[144:147], v[196:199], v[74:77]
	v_mfma_f32_16x16x32_bf16 v[70:73], v[136:139], v[208:211], v[70:73]
	v_mfma_f32_16x16x32_bf16 v[66:69], v[144:147], v[208:211], v[66:69]
	s_setprio 0
	s_setprio 1
	v_mfma_f32_16x16x32_bf16 v[30:33], v[148:151], v[164:167], v[30:33]
	v_mfma_f32_16x16x32_bf16 v[26:29], v[156:159], v[164:167], v[26:29]
	v_mfma_f32_16x16x32_bf16 v[22:25], v[148:151], v[182:185], v[22:25]
	v_mfma_f32_16x16x32_bf16 v[18:21], v[156:159], v[182:185], v[18:21]
	v_mfma_f32_16x16x32_bf16 v[14:17], v[148:151], v[192:195], v[14:17]
	v_mfma_f32_16x16x32_bf16 v[10:13], v[156:159], v[192:195], v[10:13]
	v_mfma_f32_16x16x32_bf16 v[6:9], v[148:151], v[204:207], v[6:9]
	v_mfma_f32_16x16x32_bf16 v[2:5], v[156:159], v[204:207], v[2:5]
	v_mfma_f32_16x16x32_bf16 v[30:33], v[152:155], v[178:181], v[30:33]
	v_mfma_f32_16x16x32_bf16 v[26:29], v[160:163], v[178:181], v[26:29]
	v_mfma_f32_16x16x32_bf16 v[22:25], v[152:155], v[188:191], v[22:25]
	v_mfma_f32_16x16x32_bf16 v[18:21], v[160:163], v[188:191], v[18:21]
	v_mfma_f32_16x16x32_bf16 v[14:17], v[152:155], v[196:199], v[14:17]
	v_mfma_f32_16x16x32_bf16 v[10:13], v[160:163], v[196:199], v[10:13]
	v_mfma_f32_16x16x32_bf16 v[6:9], v[152:155], v[208:211], v[6:9]
	v_mfma_f32_16x16x32_bf16 v[2:5], v[160:163], v[208:211], v[2:5]
	s_setprio 0
	s_barrier
	s_add_i32 s57, s57, 2
	s_add_u32 s33, s33, 0x100
	s_addc_u32 s56, s56, 0
	s_cmp_gt_u32 s57, 41
	s_mov_b64 s[48:49], s[50:51]
	s_cbranch_scc0 .LBB0_1529
	s_and_b64 vcc, exec, s[44:45]
	s_cbranch_vccz .LBB0_1532
	s_barrier

.LBB0_1553:
	s_add_i32 s63, s54, 2
	s_add_u32 s52, s50, 0x100
	s_addc_u32 s53, s51, 0
	s_add_i32 s64, 0, 0x10000
	s_cmp_eq_u32 s60, s54
	s_cselect_b32 s57, s45, s53
	s_cselect_b32 s56, s44, s52
	s_cselect_b32 s55, s47, s62
	s_cselect_b32 s54, s46, s61
	s_add_i32 s65, 0, 0x14000
	v_add_u32_e32 v144, s64, v198
	v_add_u32_e32 v160, s65, v198
	s_waitcnt lgkmcnt(0)
	ds_read_b128 v[132:135], v144
	ds_read_b128 v[136:139], v144 offset:1024
	ds_read_b128 v[140:143], v144 offset:2048
	ds_read_b128 v[144:147], v144 offset:3072
	ds_read_b128 v[148:151], v160
	ds_read_b128 v[152:155], v160 offset:1024
	ds_read_b128 v[156:159], v160 offset:2048
	ds_read_b128 v[160:163], v160 offset:3072
	v_lshl_add_u64 v[214:215], s[50:51], 0, v[178:179]
	s_add_i32 m0, s4, 0xc000
	ds_read_b128 v[164:167], v199
	ds_read_b128 v[168:171], v199 offset:1024
	ds_read_b128 v[182:185], v199 offset:2048
	ds_read_b128 v[186:189], v199 offset:3072
	ds_read_b128 v[190:193], v199 offset:4096
	ds_read_b128 v[194:197], v199 offset:5120
	ds_read_b128 v[204:207], v199 offset:6144
	ds_read_b128 v[208:211], v199 offset:7168
	s_setprio 1
	global_load_lds_dwordx4 v[214:215], off
	v_lshl_add_u64 v[214:215], s[50:51], 0, v[180:181]
	s_add_i32 m0, s4, 0xe000
	s_nop 0
	global_load_lds_dwordx4 v[214:215], off
	s_waitcnt vmcnt(8) lgkmcnt(0)
	s_barrier
	v_mfma_f32_16x16x32_bf16 v[128:131], v[132:135], v[164:167], v[128:131]
	v_mfma_f32_16x16x32_bf16 v[124:127], v[140:143], v[164:167], v[124:127]
	v_mfma_f32_16x16x32_bf16 v[120:123], v[132:135], v[182:185], v[120:123]
	v_mfma_f32_16x16x32_bf16 v[116:119], v[140:143], v[182:185], v[116:119]
	v_mfma_f32_16x16x32_bf16 v[104:107], v[132:135], v[190:193], v[104:107]
	v_mfma_f32_16x16x32_bf16 v[100:103], v[140:143], v[190:193], v[100:103]
	v_mfma_f32_16x16x32_bf16 v[86:89], v[132:135], v[204:207], v[86:89]
	v_mfma_f32_16x16x32_bf16 v[82:85], v[140:143], v[204:207], v[82:85]
	v_mfma_f32_16x16x32_bf16 v[128:131], v[136:139], v[168:171], v[128:131]
	v_mfma_f32_16x16x32_bf16 v[124:127], v[144:147], v[168:171], v[124:127]
	v_mfma_f32_16x16x32_bf16 v[120:123], v[136:139], v[186:189], v[120:123]
	v_mfma_f32_16x16x32_bf16 v[116:119], v[144:147], v[186:189], v[116:119]
	v_mfma_f32_16x16x32_bf16 v[104:107], v[136:139], v[194:197], v[104:107]
	v_mfma_f32_16x16x32_bf16 v[100:103], v[144:147], v[194:197], v[100:103]
	v_mfma_f32_16x16x32_bf16 v[86:89], v[136:139], v[208:211], v[86:89]
	v_mfma_f32_16x16x32_bf16 v[82:85], v[144:147], v[208:211], v[82:85]
	s_setprio 0
	s_setprio 1
	v_mfma_f32_16x16x32_bf16 v[112:115], v[148:151], v[164:167], v[112:115]
	v_mfma_f32_16x16x32_bf16 v[108:111], v[156:159], v[164:167], v[108:111]
	v_mfma_f32_16x16x32_bf16 v[94:97], v[148:151], v[182:185], v[94:97]
	v_mfma_f32_16x16x32_bf16 v[90:93], v[156:159], v[182:185], v[90:93]
	v_mfma_f32_16x16x32_bf16 v[78:81], v[148:151], v[190:193], v[78:81]
	v_mfma_f32_16x16x32_bf16 v[74:77], v[156:159], v[190:193], v[74:77]
	v_mfma_f32_16x16x32_bf16 v[70:73], v[148:151], v[204:207], v[70:73]
	v_mfma_f32_16x16x32_bf16 v[66:69], v[156:159], v[204:207], v[66:69]
	v_mfma_f32_16x16x32_bf16 v[112:115], v[152:155], v[168:171], v[112:115]
	v_mfma_f32_16x16x32_bf16 v[108:111], v[160:163], v[168:171], v[108:111]
	v_mfma_f32_16x16x32_bf16 v[94:97], v[152:155], v[186:189], v[94:97]
	v_mfma_f32_16x16x32_bf16 v[90:93], v[160:163], v[186:189], v[90:93]
	v_mfma_f32_16x16x32_bf16 v[78:81], v[152:155], v[194:197], v[78:81]
	v_mfma_f32_16x16x32_bf16 v[74:77], v[160:163], v[194:197], v[74:77]
	v_mfma_f32_16x16x32_bf16 v[70:73], v[152:155], v[208:211], v[70:73]
	v_mfma_f32_16x16x32_bf16 v[66:69], v[160:163], v[208:211], v[66:69]
	s_setprio 0
	s_barrier
	s_add_i32 s50, s64, s2
	v_lshl_add_u64 v[214:215], s[54:55], 0, v[98:99]
	s_mov_b32 m0, s50
	ds_read_b128 v[164:167], v199 offset:16384
	ds_read_b128 v[168:171], v199 offset:17408
	ds_read_b128 v[182:185], v199 offset:18432
	ds_read_b128 v[186:189], v199 offset:19456
	ds_read_b128 v[190:193], v199 offset:20480
	ds_read_b128 v[194:197], v199 offset:21504
	ds_read_b128 v[204:207], v199 offset:22528
	ds_read_b128 v[208:211], v199 offset:23552
	s_setprio 1
	global_load_lds_dwordx4 v[214:215], off
	s_add_i32 m0, s50, 0x2000
	s_add_u32 s50, s54, 0xb0000
	v_lshl_add_u64 v[216:217], s[54:55], 0, v[172:173]
	s_addc_u32 s51, s55, 0
	s_add_i32 s64, s65, s2
	global_load_lds_dwordx4 v[216:217], off
	v_lshl_add_u64 v[218:219], s[50:51], 0, v[98:99]
	s_mov_b32 m0, s64
	v_lshl_add_u64 v[220:221], s[56:57], 0, v[174:175]
	global_load_lds_dwordx4 v[218:219], off
	v_lshl_add_u64 v[218:219], s[50:51], 0, v[172:173]
	s_add_i32 m0, s64, 0x2000
	s_nop 0
	global_load_lds_dwordx4 v[218:219], off
	v_lshl_add_u64 v[218:219], s[56:57], 0, v[176:177]
	s_mov_b32 m0, s4
	s_nop 0
	global_load_lds_dwordx4 v[218:219], off
	s_mov_b32 m0, s7
	s_nop 0
	global_load_lds_dwordx4 v[220:221], off
	s_waitcnt vmcnt(8) lgkmcnt(0)
	s_barrier
	v_mfma_f32_16x16x32_bf16 v[62:65], v[132:135], v[164:167], v[62:65]
	v_mfma_f32_16x16x32_bf16 v[58:61], v[140:143], v[164:167], v[58:61]
	v_mfma_f32_16x16x32_bf16 v[54:57], v[132:135], v[182:185], v[54:57]
	v_mfma_f32_16x16x32_bf16 v[50:53], v[140:143], v[182:185], v[50:53]
	v_mfma_f32_16x16x32_bf16 v[38:41], v[132:135], v[190:193], v[38:41]
	v_mfma_f32_16x16x32_bf16 v[34:37], v[140:143], v[190:193], v[34:37]
	v_mfma_f32_16x16x32_bf16 v[22:25], v[132:135], v[204:207], v[22:25]
	v_mfma_f32_16x16x32_bf16 v[18:21], v[140:143], v[204:207], v[18:21]
	v_mfma_f32_16x16x32_bf16 v[62:65], v[136:139], v[168:171], v[62:65]
	v_mfma_f32_16x16x32_bf16 v[58:61], v[144:147], v[168:171], v[58:61]
	v_mfma_f32_16x16x32_bf16 v[54:57], v[136:139], v[186:189], v[54:57]
	v_mfma_f32_16x16x32_bf16 v[50:53], v[144:147], v[186:189], v[50:53]
	v_mfma_f32_16x16x32_bf16 v[38:41], v[136:139], v[194:197], v[38:41]
	v_mfma_f32_16x16x32_bf16 v[34:37], v[144:147], v[194:197], v[34:37]
	v_mfma_f32_16x16x32_bf16 v[22:25], v[136:139], v[208:211], v[22:25]
	v_mfma_f32_16x16x32_bf16 v[18:21], v[144:147], v[208:211], v[18:21]
	s_setprio 0
	s_setprio 1
	v_mfma_f32_16x16x32_bf16 v[46:49], v[148:151], v[164:167], v[46:49]
	v_mfma_f32_16x16x32_bf16 v[42:45], v[156:159], v[164:167], v[42:45]
	v_mfma_f32_16x16x32_bf16 v[30:33], v[148:151], v[182:185], v[30:33]
	v_mfma_f32_16x16x32_bf16 v[26:29], v[156:159], v[182:185], v[26:29]
	v_mfma_f32_16x16x32_bf16 v[14:17], v[148:151], v[190:193], v[14:17]
	v_mfma_f32_16x16x32_bf16 v[10:13], v[156:159], v[190:193], v[10:13]
	v_mfma_f32_16x16x32_bf16 v[6:9], v[148:151], v[204:207], v[6:9]
	v_mfma_f32_16x16x32_bf16 v[2:5], v[156:159], v[204:207], v[2:5]
	v_mfma_f32_16x16x32_bf16 v[46:49], v[152:155], v[168:171], v[46:49]
	v_mfma_f32_16x16x32_bf16 v[42:45], v[160:163], v[168:171], v[42:45]
	v_mfma_f32_16x16x32_bf16 v[30:33], v[152:155], v[186:189], v[30:33]
	v_mfma_f32_16x16x32_bf16 v[26:29], v[160:163], v[186:189], v[26:29]
	v_mfma_f32_16x16x32_bf16 v[14:17], v[152:155], v[194:197], v[14:17]
	v_mfma_f32_16x16x32_bf16 v[10:13], v[160:163], v[194:197], v[10:13]
	v_mfma_f32_16x16x32_bf16 v[6:9], v[152:155], v[208:211], v[6:9]
	v_mfma_f32_16x16x32_bf16 v[2:5], v[160:163], v[208:211], v[2:5]
	s_setprio 0
	s_barrier
	s_add_i32 s64, 0, 0x18000
	s_add_i32 s65, 0, 0x1c000
	v_add_u32_e32 v144, s64, v198
	v_add_u32_e32 v160, s65, v198
	ds_read_b128 v[132:135], v144
	ds_read_b128 v[136:139], v144 offset:1024
	ds_read_b128 v[140:143], v144 offset:2048
	ds_read_b128 v[144:147], v144 offset:3072
	ds_read_b128 v[148:151], v160
	ds_read_b128 v[152:155], v160 offset:1024
	ds_read_b128 v[156:159], v160 offset:2048
	ds_read_b128 v[160:163], v160 offset:3072
	s_add_u32 s50, s56, 0xb0000
	s_addc_u32 s51, s57, 0
	s_mov_b32 m0, s8
	v_lshl_add_u64 v[222:223], s[50:51], 0, v[176:177]
	ds_read_b128 v[164:167], v199 offset:32768
	ds_read_b128 v[168:171], v199 offset:33792
	ds_read_b128 v[182:185], v199 offset:34816
	ds_read_b128 v[186:189], v199 offset:35840
	ds_read_b128 v[190:193], v199 offset:36864
	ds_read_b128 v[194:197], v199 offset:37888
	ds_read_b128 v[204:207], v199 offset:38912
	ds_read_b128 v[208:211], v199 offset:39936
	s_setprio 1
	global_load_lds_dwordx4 v[222:223], off
	v_lshl_add_u64 v[222:223], s[50:51], 0, v[174:175]
	s_mov_b32 m0, s9
	s_nop 0
	global_load_lds_dwordx4 v[222:223], off
	s_waitcnt vmcnt(8) lgkmcnt(0)
	s_barrier
	v_mfma_f32_16x16x32_bf16 v[128:131], v[132:135], v[164:167], v[128:131]
	v_mfma_f32_16x16x32_bf16 v[124:127], v[140:143], v[164:167], v[124:127]
	v_mfma_f32_16x16x32_bf16 v[120:123], v[132:135], v[182:185], v[120:123]
	v_mfma_f32_16x16x32_bf16 v[116:119], v[140:143], v[182:185], v[116:119]
	v_mfma_f32_16x16x32_bf16 v[104:107], v[132:135], v[190:193], v[104:107]
	v_mfma_f32_16x16x32_bf16 v[100:103], v[140:143], v[190:193], v[100:103]
	v_mfma_f32_16x16x32_bf16 v[86:89], v[132:135], v[204:207], v[86:89]
	v_mfma_f32_16x16x32_bf16 v[82:85], v[140:143], v[204:207], v[82:85]
	v_mfma_f32_16x16x32_bf16 v[128:131], v[136:139], v[168:171], v[128:131]
	v_mfma_f32_16x16x32_bf16 v[124:127], v[144:147], v[168:171], v[124:127]
	v_mfma_f32_16x16x32_bf16 v[120:123], v[136:139], v[186:189], v[120:123]
	v_mfma_f32_16x16x32_bf16 v[116:119], v[144:147], v[186:189], v[116:119]
	v_mfma_f32_16x16x32_bf16 v[104:107], v[136:139], v[194:197], v[104:107]
	v_mfma_f32_16x16x32_bf16 v[100:103], v[144:147], v[194:197], v[100:103]
	v_mfma_f32_16x16x32_bf16 v[86:89], v[136:139], v[208:211], v[86:89]
	v_mfma_f32_16x16x32_bf16 v[82:85], v[144:147], v[208:211], v[82:85]
	s_setprio 0
	s_setprio 1
	v_mfma_f32_16x16x32_bf16 v[112:115], v[148:151], v[164:167], v[112:115]
	v_mfma_f32_16x16x32_bf16 v[108:111], v[156:159], v[164:167], v[108:111]
	v_mfma_f32_16x16x32_bf16 v[94:97], v[148:151], v[182:185], v[94:97]
	v_mfma_f32_16x16x32_bf16 v[90:93], v[156:159], v[182:185], v[90:93]
	v_mfma_f32_16x16x32_bf16 v[78:81], v[148:151], v[190:193], v[78:81]
	v_mfma_f32_16x16x32_bf16 v[74:77], v[156:159], v[190:193], v[74:77]
	v_mfma_f32_16x16x32_bf16 v[70:73], v[148:151], v[204:207], v[70:73]
	v_mfma_f32_16x16x32_bf16 v[66:69], v[156:159], v[204:207], v[66:69]
	v_mfma_f32_16x16x32_bf16 v[112:115], v[152:155], v[168:171], v[112:115]
	v_mfma_f32_16x16x32_bf16 v[108:111], v[160:163], v[168:171], v[108:111]
	v_mfma_f32_16x16x32_bf16 v[94:97], v[152:155], v[186:189], v[94:97]
	v_mfma_f32_16x16x32_bf16 v[90:93], v[160:163], v[186:189], v[90:93]
	v_mfma_f32_16x16x32_bf16 v[78:81], v[152:155], v[194:197], v[78:81]
	v_mfma_f32_16x16x32_bf16 v[74:77], v[160:163], v[194:197], v[74:77]
	v_mfma_f32_16x16x32_bf16 v[70:73], v[152:155], v[208:211], v[70:73]
	v_mfma_f32_16x16x32_bf16 v[66:69], v[160:163], v[208:211], v[66:69]
	s_setprio 0
	s_barrier
	s_add_i32 s50, s64, s2
	v_lshl_add_u64 v[214:215], v[214:215], 0, s[28:29]
	s_mov_b32 m0, s50
	ds_read_b128 v[164:167], v199 offset:49152
	ds_read_b128 v[168:171], v199 offset:50176
	ds_read_b128 v[182:185], v199 offset:51200
	ds_read_b128 v[186:189], v199 offset:52224
	ds_read_b128 v[190:193], v199 offset:53248
	ds_read_b128 v[194:197], v199 offset:54272
	ds_read_b128 v[204:207], v199 offset:55296
	ds_read_b128 v[208:211], v199 offset:56320
	s_setprio 1
	global_load_lds_dwordx4 v[214:215], off
	s_add_i32 m0, s50, 0x2000
	s_add_u32 s50, s54, 0xb0080
	v_lshl_add_u64 v[214:215], v[216:217], 0, s[28:29]
	s_addc_u32 s51, s55, 0
	s_add_i32 s54, s65, s2
	global_load_lds_dwordx4 v[214:215], off
	v_lshl_add_u64 v[214:215], s[50:51], 0, v[98:99]
	s_mov_b32 m0, s54
	s_nop 0
	global_load_lds_dwordx4 v[214:215], off
	v_lshl_add_u64 v[214:215], s[50:51], 0, v[172:173]
	s_add_i32 m0, s54, 0x2000
	s_nop 0
	global_load_lds_dwordx4 v[214:215], off
	v_lshl_add_u64 v[214:215], v[218:219], 0, s[28:29]
	s_mov_b32 m0, s12
	s_nop 0
	global_load_lds_dwordx4 v[214:215], off
	v_lshl_add_u64 v[214:215], v[220:221], 0, s[28:29]
	s_mov_b32 m0, s13
	s_nop 0
	global_load_lds_dwordx4 v[214:215], off
	s_waitcnt vmcnt(8) lgkmcnt(0)
	s_barrier
	v_mfma_f32_16x16x32_bf16 v[62:65], v[132:135], v[164:167], v[62:65]
	v_mfma_f32_16x16x32_bf16 v[58:61], v[140:143], v[164:167], v[58:61]
	v_mfma_f32_16x16x32_bf16 v[54:57], v[132:135], v[182:185], v[54:57]
	v_mfma_f32_16x16x32_bf16 v[50:53], v[140:143], v[182:185], v[50:53]
	v_mfma_f32_16x16x32_bf16 v[38:41], v[132:135], v[190:193], v[38:41]
	v_mfma_f32_16x16x32_bf16 v[34:37], v[140:143], v[190:193], v[34:37]
	v_mfma_f32_16x16x32_bf16 v[22:25], v[132:135], v[204:207], v[22:25]
	v_mfma_f32_16x16x32_bf16 v[18:21], v[140:143], v[204:207], v[18:21]
	v_mfma_f32_16x16x32_bf16 v[62:65], v[136:139], v[168:171], v[62:65]
	v_mfma_f32_16x16x32_bf16 v[58:61], v[144:147], v[168:171], v[58:61]
	v_mfma_f32_16x16x32_bf16 v[54:57], v[136:139], v[186:189], v[54:57]
	v_mfma_f32_16x16x32_bf16 v[50:53], v[144:147], v[186:189], v[50:53]
	v_mfma_f32_16x16x32_bf16 v[38:41], v[136:139], v[194:197], v[38:41]
	v_mfma_f32_16x16x32_bf16 v[34:37], v[144:147], v[194:197], v[34:37]
	v_mfma_f32_16x16x32_bf16 v[22:25], v[136:139], v[208:211], v[22:25]
	v_mfma_f32_16x16x32_bf16 v[18:21], v[144:147], v[208:211], v[18:21]
	s_setprio 0
	s_setprio 1
	v_mfma_f32_16x16x32_bf16 v[46:49], v[148:151], v[164:167], v[46:49]
	v_mfma_f32_16x16x32_bf16 v[42:45], v[156:159], v[164:167], v[42:45]
	v_mfma_f32_16x16x32_bf16 v[30:33], v[148:151], v[182:185], v[30:33]
	v_mfma_f32_16x16x32_bf16 v[26:29], v[156:159], v[182:185], v[26:29]
	v_mfma_f32_16x16x32_bf16 v[14:17], v[148:151], v[190:193], v[14:17]
	v_mfma_f32_16x16x32_bf16 v[10:13], v[156:159], v[190:193], v[10:13]
	v_mfma_f32_16x16x32_bf16 v[6:9], v[148:151], v[204:207], v[6:9]
	v_mfma_f32_16x16x32_bf16 v[2:5], v[156:159], v[204:207], v[2:5]
	v_mfma_f32_16x16x32_bf16 v[46:49], v[152:155], v[168:171], v[46:49]
	v_mfma_f32_16x16x32_bf16 v[42:45], v[160:163], v[168:171], v[42:45]
	v_mfma_f32_16x16x32_bf16 v[30:33], v[152:155], v[186:189], v[30:33]
	v_mfma_f32_16x16x32_bf16 v[26:29], v[160:163], v[186:189], v[26:29]
	v_mfma_f32_16x16x32_bf16 v[14:17], v[152:155], v[194:197], v[14:17]
	v_mfma_f32_16x16x32_bf16 v[10:13], v[160:163], v[194:197], v[10:13]
	v_mfma_f32_16x16x32_bf16 v[6:9], v[152:155], v[208:211], v[6:9]
	v_mfma_f32_16x16x32_bf16 v[2:5], v[160:163], v[208:211], v[2:5]
	s_setprio 0
	s_barrier
	s_add_u32 s61, s61, 0x100
	s_addc_u32 s62, s62, 0
	s_cmp_ge_i32 s63, s59
	s_mov_b64 s[50:51], s[52:53]
	s_mov_b32 s54, s63
	s_cbranch_scc0 .LBB0_1553
	s_and_b64 vcc, exec, s[42:43]
	s_cbranch_vccz .LBB0_1556
	s_barrier
